# hand-written staged epilogue also for the NK tiles of NA G1 (kv-row mapping, f32 state for ctx rows)
# baseline (speedup 1.0000x reference)
.Lgm_ph13_loop:
	s_waitcnt lgkmcnt(1)
	v_mfma_f32_32x32x16_bf16 v[82:97], v[240:243], v[252:255], v[82:97]
	ds_read_b128 v[220:223], v210 offset:0
	s_add_u32 m0, s81, 0x5000
	s_nop 0
	global_load_lds_dwordx4 v202, s[70:71]
	v_mfma_f32_32x32x16_bf16 v[66:81], v[236:239], v[252:255], v[66:81]
	ds_read_b128 v[232:235], v214 offset:0
	s_add_u32 m0, s82, 0x0
	s_nop 0
	global_load_lds_dwordx4 v207, s[72:73]
	v_mfma_f32_32x32x16_bf16 v[50:65], v[240:243], v[248:251], v[50:65]
	ds_read_b128 v[216:219], v210 offset:4096
	s_add_u32 m0, s82, 0x1000
	s_nop 0
	global_load_lds_dwordx4 v206, s[72:73]
	v_mfma_f32_32x32x16_bf16 v[34:49], v[236:239], v[248:251], v[34:49]
	ds_read_b128 v[228:231], v214 offset:4096
	s_add_u32 m0, s82, 0x2000
	s_nop 0
	global_load_lds_dwordx4 v205, s[72:73]
	s_waitcnt lgkmcnt(4)
	v_mfma_f32_32x32x16_bf16 v[18:33], v[240:243], v[244:247], v[18:33]
	ds_read_b128 v[224:227], v214 offset:8192
	v_mfma_f32_32x32x16_bf16 v[2:17], v[236:239], v[244:247], v[2:17]
	s_add_u32 m0, s82, 0x3000
	s_nop 0
	global_load_lds_dwordx4 v204, s[72:73]
	s_waitcnt lgkmcnt(1)
	v_mfma_f32_32x32x16_bf16 v[82:97], v[220:223], v[232:235], v[82:97]
	ds_read_b128 v[240:243], v209 offset:0
	v_mfma_f32_32x32x16_bf16 v[66:81], v[216:219], v[232:235], v[66:81]
	ds_read_b128 v[252:255], v213 offset:0
	v_mfma_f32_32x32x16_bf16 v[50:65], v[220:223], v[228:231], v[50:65]
	ds_read_b128 v[236:239], v209 offset:4096
	v_mfma_f32_32x32x16_bf16 v[34:49], v[216:219], v[228:231], v[34:49]
	ds_read_b128 v[248:251], v213 offset:4096
	s_waitcnt lgkmcnt(4)
	v_mfma_f32_32x32x16_bf16 v[18:33], v[220:223], v[224:227], v[18:33]
	ds_read_b128 v[244:247], v213 offset:8192
	v_mfma_f32_32x32x16_bf16 v[2:17], v[216:219], v[224:227], v[2:17]
	s_waitcnt lgkmcnt(1)
	v_mfma_f32_32x32x16_bf16 v[82:97], v[240:243], v[252:255], v[82:97]
	ds_read_b128 v[220:223], v208 offset:0
	s_add_u32 s83, s79, s78
	s_add_u32 s83, s83, 2
	s_and_b32 s83, s83, 15
	v_mfma_f32_32x32x16_bf16 v[66:81], v[236:239], v[252:255], v[66:81]
	ds_read_b128 v[232:235], v212 offset:0
	s_lshl_b32 s83, s83, 7
	s_add_u32 s70, s66, s83
	v_mfma_f32_32x32x16_bf16 v[50:65], v[240:243], v[248:251], v[50:65]
	ds_read_b128 v[216:219], v208 offset:4096
	s_addc_u32 s71, s67, 0
	s_add_u32 s72, s68, s83
	v_mfma_f32_32x32x16_bf16 v[34:49], v[236:239], v[248:251], v[34:49]
	ds_read_b128 v[228:231], v212 offset:4096
	s_addc_u32 s73, s69, 0
	s_add_u32 s81, s80, 0x0
	s_add_u32 s82, s80, 0xc000
	s_waitcnt lgkmcnt(4)
	v_mfma_f32_32x32x16_bf16 v[18:33], v[240:243], v[244:247], v[18:33]
	ds_read_b128 v[224:227], v212 offset:8192
	v_mfma_f32_32x32x16_bf16 v[2:17], v[236:239], v[244:247], v[2:17]
	s_waitcnt vmcnt(0) lgkmcnt(0)
	s_barrier
	v_mfma_f32_32x32x16_bf16 v[82:97], v[220:223], v[232:235], v[82:97]
	s_add_u32 m0, s81, 0x0
	ds_read_b128 v[240:243], v211 offset:16384
	global_load_lds_dwordx4 v207, s[70:71]
	v_mfma_f32_32x32x16_bf16 v[66:81], v[216:219], v[232:235], v[66:81]
	s_add_u32 m0, s81, 0x1000
	ds_read_b128 v[252:255], v215 offset:24576
	global_load_lds_dwordx4 v206, s[70:71]
	v_mfma_f32_32x32x16_bf16 v[50:65], v[220:223], v[228:231], v[50:65]
	s_add_u32 m0, s81, 0x2000
	ds_read_b128 v[236:239], v211 offset:20480
	global_load_lds_dwordx4 v205, s[70:71]
	v_mfma_f32_32x32x16_bf16 v[34:49], v[216:219], v[228:231], v[34:49]
	s_add_u32 m0, s81, 0x3000
	ds_read_b128 v[248:251], v215 offset:28672
	global_load_lds_dwordx4 v204, s[70:71]
	v_mfma_f32_32x32x16_bf16 v[18:33], v[220:223], v[224:227], v[18:33]
	s_add_u32 m0, s81, 0x4000
	ds_read_b128 v[244:247], v215 offset:32768
	global_load_lds_dwordx4 v203, s[70:71]
	v_mfma_f32_32x32x16_bf16 v[2:17], v[216:219], v[224:227], v[2:17]
	s_waitcnt lgkmcnt(1)
	v_mfma_f32_32x32x16_bf16 v[82:97], v[240:243], v[252:255], v[82:97]
	ds_read_b128 v[220:223], v210 offset:16384
	s_add_u32 m0, s81, 0x5000
	s_nop 0
	global_load_lds_dwordx4 v202, s[70:71]
	v_mfma_f32_32x32x16_bf16 v[66:81], v[236:239], v[252:255], v[66:81]
	ds_read_b128 v[232:235], v214 offset:24576
	s_add_u32 m0, s82, 0x0
	s_nop 0
	global_load_lds_dwordx4 v207, s[72:73]
	v_mfma_f32_32x32x16_bf16 v[50:65], v[240:243], v[248:251], v[50:65]
	ds_read_b128 v[216:219], v210 offset:20480
	s_add_u32 m0, s82, 0x1000
	s_nop 0
	global_load_lds_dwordx4 v206, s[72:73]
	v_mfma_f32_32x32x16_bf16 v[34:49], v[236:239], v[248:251], v[34:49]
	ds_read_b128 v[228:231], v214 offset:28672
	s_add_u32 m0, s82, 0x2000
	s_nop 0
	global_load_lds_dwordx4 v205, s[72:73]
	s_waitcnt lgkmcnt(4)
	v_mfma_f32_32x32x16_bf16 v[18:33], v[240:243], v[244:247], v[18:33]
	ds_read_b128 v[224:227], v214 offset:32768
	v_mfma_f32_32x32x16_bf16 v[2:17], v[236:239], v[244:247], v[2:17]
	s_add_u32 m0, s82, 0x3000
	s_nop 0
	global_load_lds_dwordx4 v204, s[72:73]
	s_waitcnt lgkmcnt(1)
	v_mfma_f32_32x32x16_bf16 v[82:97], v[220:223], v[232:235], v[82:97]
	ds_read_b128 v[240:243], v209 offset:16384
	v_mfma_f32_32x32x16_bf16 v[66:81], v[216:219], v[232:235], v[66:81]
	ds_read_b128 v[252:255], v213 offset:24576
	v_mfma_f32_32x32x16_bf16 v[50:65], v[220:223], v[228:231], v[50:65]
	ds_read_b128 v[236:239], v209 offset:20480
	v_mfma_f32_32x32x16_bf16 v[34:49], v[216:219], v[228:231], v[34:49]
	ds_read_b128 v[248:251], v213 offset:28672
	s_waitcnt lgkmcnt(4)
	v_mfma_f32_32x32x16_bf16 v[18:33], v[220:223], v[224:227], v[18:33]
	ds_read_b128 v[244:247], v213 offset:32768
	v_mfma_f32_32x32x16_bf16 v[2:17], v[216:219], v[224:227], v[2:17]
	s_waitcnt lgkmcnt(1)
	v_mfma_f32_32x32x16_bf16 v[82:97], v[240:243], v[252:255], v[82:97]
	ds_read_b128 v[220:223], v208 offset:16384
	s_add_u32 s83, s79, s78
	s_add_u32 s83, s83, 3
	s_and_b32 s83, s83, 15
	v_mfma_f32_32x32x16_bf16 v[66:81], v[236:239], v[252:255], v[66:81]
	ds_read_b128 v[232:235], v212 offset:24576
	s_lshl_b32 s83, s83, 7
	s_add_u32 s70, s66, s83
	v_mfma_f32_32x32x16_bf16 v[50:65], v[240:243], v[248:251], v[50:65]
	ds_read_b128 v[216:219], v208 offset:20480
	s_addc_u32 s71, s67, 0
	s_add_u32 s72, s68, s83
	v_mfma_f32_32x32x16_bf16 v[34:49], v[236:239], v[248:251], v[34:49]
	ds_read_b128 v[228:231], v212 offset:28672
	s_addc_u32 s73, s69, 0
	s_add_u32 s81, s80, 0x6000
	s_add_u32 s82, s80, 0x10000
	s_waitcnt lgkmcnt(4)
	v_mfma_f32_32x32x16_bf16 v[18:33], v[240:243], v[244:247], v[18:33]
	ds_read_b128 v[224:227], v212 offset:32768
	v_mfma_f32_32x32x16_bf16 v[2:17], v[236:239], v[244:247], v[2:17]
	s_waitcnt vmcnt(0) lgkmcnt(0)
	s_barrier
	v_mfma_f32_32x32x16_bf16 v[82:97], v[220:223], v[232:235], v[82:97]
	s_add_u32 m0, s81, 0x0
	ds_read_b128 v[240:243], v211 offset:0
	global_load_lds_dwordx4 v207, s[70:71]
	v_mfma_f32_32x32x16_bf16 v[66:81], v[216:219], v[232:235], v[66:81]
	s_add_u32 m0, s81, 0x1000
	ds_read_b128 v[252:255], v215 offset:0
	global_load_lds_dwordx4 v206, s[70:71]
	v_mfma_f32_32x32x16_bf16 v[50:65], v[220:223], v[228:231], v[50:65]
	s_add_u32 m0, s81, 0x2000
	ds_read_b128 v[236:239], v211 offset:4096
	global_load_lds_dwordx4 v205, s[70:71]
	v_mfma_f32_32x32x16_bf16 v[34:49], v[216:219], v[228:231], v[34:49]
	s_add_u32 m0, s81, 0x3000
	ds_read_b128 v[248:251], v215 offset:4096
	global_load_lds_dwordx4 v204, s[70:71]
	v_mfma_f32_32x32x16_bf16 v[18:33], v[220:223], v[224:227], v[18:33]
	s_add_u32 m0, s81, 0x4000
	ds_read_b128 v[244:247], v215 offset:8192
	global_load_lds_dwordx4 v203, s[70:71]
	v_mfma_f32_32x32x16_bf16 v[2:17], v[216:219], v[224:227], v[2:17]
	s_add_u32 s78, s78, 2
	s_cmp_lt_u32 s78, 14
	s_cbranch_scc1 .Lgm_ph13_loop
	s_waitcnt lgkmcnt(1)
	v_mfma_f32_32x32x16_bf16 v[82:97], v[240:243], v[252:255], v[82:97]
	ds_read_b128 v[220:223], v210 offset:0
	s_add_u32 m0, s81, 0x5000
	s_nop 0
	global_load_lds_dwordx4 v202, s[70:71]
	v_mfma_f32_32x32x16_bf16 v[66:81], v[236:239], v[252:255], v[66:81]
	ds_read_b128 v[232:235], v214 offset:0
	s_add_u32 m0, s82, 0x0
	s_nop 0
	global_load_lds_dwordx4 v207, s[72:73]
	v_mfma_f32_32x32x16_bf16 v[50:65], v[240:243], v[248:251], v[50:65]
	ds_read_b128 v[216:219], v210 offset:4096
	s_add_u32 m0, s82, 0x1000
	s_nop 0
	global_load_lds_dwordx4 v206, s[72:73]
	v_mfma_f32_32x32x16_bf16 v[34:49], v[236:239], v[248:251], v[34:49]
	ds_read_b128 v[228:231], v214 offset:4096
	s_add_u32 m0, s82, 0x2000
	s_nop 0
	global_load_lds_dwordx4 v205, s[72:73]
	s_waitcnt lgkmcnt(4)
	v_mfma_f32_32x32x16_bf16 v[18:33], v[240:243], v[244:247], v[18:33]
	ds_read_b128 v[224:227], v214 offset:8192
	v_mfma_f32_32x32x16_bf16 v[2:17], v[236:239], v[244:247], v[2:17]
	s_add_u32 m0, s82, 0x3000
	s_nop 0
	global_load_lds_dwordx4 v204, s[72:73]
	s_waitcnt lgkmcnt(1)
	v_mfma_f32_32x32x16_bf16 v[82:97], v[220:223], v[232:235], v[82:97]
	ds_read_b128 v[240:243], v209 offset:0
	v_mfma_f32_32x32x16_bf16 v[66:81], v[216:219], v[232:235], v[66:81]
	ds_read_b128 v[252:255], v213 offset:0
	v_mfma_f32_32x32x16_bf16 v[50:65], v[220:223], v[228:231], v[50:65]
	ds_read_b128 v[236:239], v209 offset:4096
	v_mfma_f32_32x32x16_bf16 v[34:49], v[216:219], v[228:231], v[34:49]
	ds_read_b128 v[248:251], v213 offset:4096
	s_waitcnt lgkmcnt(4)
	v_mfma_f32_32x32x16_bf16 v[18:33], v[220:223], v[224:227], v[18:33]
	ds_read_b128 v[244:247], v213 offset:8192
	v_mfma_f32_32x32x16_bf16 v[2:17], v[216:219], v[224:227], v[2:17]
	s_waitcnt lgkmcnt(1)
	v_mfma_f32_32x32x16_bf16 v[82:97], v[240:243], v[252:255], v[82:97]
	ds_read_b128 v[220:223], v208 offset:0
	v_mfma_f32_32x32x16_bf16 v[66:81], v[236:239], v[252:255], v[66:81]
	ds_read_b128 v[232:235], v212 offset:0
	v_mfma_f32_32x32x16_bf16 v[50:65], v[240:243], v[248:251], v[50:65]
	ds_read_b128 v[216:219], v208 offset:4096
	v_mfma_f32_32x32x16_bf16 v[34:49], v[236:239], v[248:251], v[34:49]
	ds_read_b128 v[228:231], v212 offset:4096
	s_waitcnt lgkmcnt(4)
	v_mfma_f32_32x32x16_bf16 v[18:33], v[240:243], v[244:247], v[18:33]
	ds_read_b128 v[224:227], v212 offset:8192
	v_mfma_f32_32x32x16_bf16 v[2:17], v[236:239], v[244:247], v[2:17]
	s_waitcnt vmcnt(0) lgkmcnt(0)
	s_barrier
	v_mfma_f32_32x32x16_bf16 v[82:97], v[220:223], v[232:235], v[82:97]
	ds_read_b128 v[240:243], v211 offset:16384
	v_mfma_f32_32x32x16_bf16 v[66:81], v[216:219], v[232:235], v[66:81]
	ds_read_b128 v[252:255], v215 offset:24576
	v_mfma_f32_32x32x16_bf16 v[50:65], v[220:223], v[228:231], v[50:65]
	ds_read_b128 v[236:239], v211 offset:20480
	v_mfma_f32_32x32x16_bf16 v[34:49], v[216:219], v[228:231], v[34:49]
	ds_read_b128 v[248:251], v215 offset:28672
	v_mfma_f32_32x32x16_bf16 v[18:33], v[220:223], v[224:227], v[18:33]
	ds_read_b128 v[244:247], v215 offset:32768
	v_mfma_f32_32x32x16_bf16 v[2:17], v[216:219], v[224:227], v[2:17]
	s_waitcnt lgkmcnt(1)
	v_mfma_f32_32x32x16_bf16 v[82:97], v[240:243], v[252:255], v[82:97]
	ds_read_b128 v[220:223], v210 offset:16384
	v_mfma_f32_32x32x16_bf16 v[66:81], v[236:239], v[252:255], v[66:81]
	ds_read_b128 v[232:235], v214 offset:24576
	v_mfma_f32_32x32x16_bf16 v[50:65], v[240:243], v[248:251], v[50:65]
	ds_read_b128 v[216:219], v210 offset:20480
	v_mfma_f32_32x32x16_bf16 v[34:49], v[236:239], v[248:251], v[34:49]
	ds_read_b128 v[228:231], v214 offset:28672
	s_waitcnt lgkmcnt(4)
	v_mfma_f32_32x32x16_bf16 v[18:33], v[240:243], v[244:247], v[18:33]
	ds_read_b128 v[224:227], v214 offset:32768
	v_mfma_f32_32x32x16_bf16 v[2:17], v[236:239], v[244:247], v[2:17]
	s_waitcnt lgkmcnt(1)
	v_mfma_f32_32x32x16_bf16 v[82:97], v[220:223], v[232:235], v[82:97]
	ds_read_b128 v[240:243], v209 offset:16384
	v_mfma_f32_32x32x16_bf16 v[66:81], v[216:219], v[232:235], v[66:81]
	ds_read_b128 v[252:255], v213 offset:24576
	v_mfma_f32_32x32x16_bf16 v[50:65], v[220:223], v[228:231], v[50:65]
	ds_read_b128 v[236:239], v209 offset:20480
	v_mfma_f32_32x32x16_bf16 v[34:49], v[216:219], v[228:231], v[34:49]
	ds_read_b128 v[248:251], v213 offset:28672
	s_waitcnt lgkmcnt(4)
	v_mfma_f32_32x32x16_bf16 v[18:33], v[220:223], v[224:227], v[18:33]
	ds_read_b128 v[244:247], v213 offset:32768
	v_mfma_f32_32x32x16_bf16 v[2:17], v[216:219], v[224:227], v[2:17]
	s_waitcnt lgkmcnt(1)
	v_mfma_f32_32x32x16_bf16 v[82:97], v[240:243], v[252:255], v[82:97]
	ds_read_b128 v[220:223], v208 offset:16384
	v_mfma_f32_32x32x16_bf16 v[66:81], v[236:239], v[252:255], v[66:81]
	ds_read_b128 v[232:235], v212 offset:24576
	v_mfma_f32_32x32x16_bf16 v[50:65], v[240:243], v[248:251], v[50:65]
	ds_read_b128 v[216:219], v208 offset:20480
	v_mfma_f32_32x32x16_bf16 v[34:49], v[236:239], v[248:251], v[34:49]
	ds_read_b128 v[228:231], v212 offset:28672
	s_waitcnt lgkmcnt(4)
	v_mfma_f32_32x32x16_bf16 v[18:33], v[240:243], v[244:247], v[18:33]
	ds_read_b128 v[224:227], v212 offset:32768
	v_mfma_f32_32x32x16_bf16 v[2:17], v[236:239], v[244:247], v[2:17]
	s_waitcnt vmcnt(0) lgkmcnt(0)
	s_barrier
	v_mfma_f32_32x32x16_bf16 v[82:97], v[220:223], v[232:235], v[82:97]
	v_mfma_f32_32x32x16_bf16 v[66:81], v[216:219], v[232:235], v[66:81]
	v_mfma_f32_32x32x16_bf16 v[50:65], v[220:223], v[228:231], v[50:65]
	v_mfma_f32_32x32x16_bf16 v[34:49], v[216:219], v[228:231], v[34:49]
	v_mfma_f32_32x32x16_bf16 v[18:33], v[220:223], v[224:227], v[18:33]
	v_mfma_f32_32x32x16_bf16 v[2:17], v[216:219], v[224:227], v[2:17]
	s_nop 7
	s_nop 7
	s_setprio 0
	s_lshr_b32 s84, s64, 6
	s_cmp_lt_u32 s84, 8
	s_cbranch_scc1 G1E_ph13_U
	s_cmp_lt_u32 s84, 16
	s_cbranch_scc1 G1E_ph13_NK
	s_cmp_lt_u32 s84, 24
	s_cbranch_scc1 G1E_ph13_ORIG
	s_load_dwordx2 s[82:83], s[0:1], 0x98
	v_mul_f32_e32 v198, 0xbfb8aa3b, v2
	v_mul_f32_e32 v199, 0xbfb8aa3b, v3
	v_mul_f32_e32 v200, 0xbfb8aa3b, v4
	v_mul_f32_e32 v201, 0xbfb8aa3b, v5
	v_exp_f32_e32 v198, v198
	v_exp_f32_e32 v199, v199
	v_exp_f32_e32 v200, v200
	v_exp_f32_e32 v201, v201
	s_nop 0
	v_add_f32_e32 v198, 1.0, v198
	v_add_f32_e32 v199, 1.0, v199
	v_add_f32_e32 v200, 1.0, v200
	v_add_f32_e32 v201, 1.0, v201
	v_div_scale_f32 v202, s[84:85], v198, v198, v2
	v_div_scale_f32 v203, s[84:85], v199, v199, v3
	v_div_scale_f32 v204, s[84:85], v200, v200, v4
	v_div_scale_f32 v205, s[84:85], v201, v201, v5
	v_rcp_f32_e32 v206, v202
	v_rcp_f32_e32 v207, v203
	v_rcp_f32_e32 v208, v204
	v_rcp_f32_e32 v209, v205
	s_nop 0
	v_div_scale_f32 v210, vcc, v2, v198, v2
	v_fma_f32 v212, -v202, v206, 1.0
	v_fmac_f32_e32 v206, v212, v206
	v_mul_f32_e32 v211, v210, v206
	v_fma_f32 v212, -v202, v211, v210
	v_fmac_f32_e32 v211, v212, v206
	v_fma_f32 v212, -v202, v211, v210
	v_div_fmas_f32 v212, v212, v206, v211
	v_div_fixup_f32 v2, v212, v198, v2
	v_div_scale_f32 v210, vcc, v3, v199, v3
	v_fma_f32 v212, -v203, v207, 1.0
	v_fmac_f32_e32 v207, v212, v207
	v_mul_f32_e32 v211, v210, v207
	v_fma_f32 v212, -v203, v211, v210
	v_fmac_f32_e32 v211, v212, v207
	v_fma_f32 v212, -v203, v211, v210
	v_div_fmas_f32 v212, v212, v207, v211
	v_div_fixup_f32 v3, v212, v199, v3
	v_div_scale_f32 v210, vcc, v4, v200, v4
	v_fma_f32 v212, -v204, v208, 1.0
	v_fmac_f32_e32 v208, v212, v208
	v_mul_f32_e32 v211, v210, v208
	v_fma_f32 v212, -v204, v211, v210
	v_fmac_f32_e32 v211, v212, v208
	v_fma_f32 v212, -v204, v211, v210
	v_div_fmas_f32 v212, v212, v208, v211
	v_div_fixup_f32 v4, v212, v200, v4
	v_div_scale_f32 v210, vcc, v5, v201, v5
	v_fma_f32 v212, -v205, v209, 1.0
	v_fmac_f32_e32 v209, v212, v209
	v_mul_f32_e32 v211, v210, v209
	v_fma_f32 v212, -v205, v211, v210
	v_fmac_f32_e32 v211, v212, v209
	v_fma_f32 v212, -v205, v211, v210
	v_div_fmas_f32 v212, v212, v209, v211
	v_div_fixup_f32 v5, v212, v201, v5
	v_mul_f32_e32 v198, 0xbfb8aa3b, v6
	v_mul_f32_e32 v199, 0xbfb8aa3b, v7
	v_mul_f32_e32 v200, 0xbfb8aa3b, v8
	v_mul_f32_e32 v201, 0xbfb8aa3b, v9
	v_exp_f32_e32 v198, v198
	v_exp_f32_e32 v199, v199
	v_exp_f32_e32 v200, v200
	v_exp_f32_e32 v201, v201
	s_nop 0
	v_add_f32_e32 v198, 1.0, v198
	v_add_f32_e32 v199, 1.0, v199
	v_add_f32_e32 v200, 1.0, v200
	v_add_f32_e32 v201, 1.0, v201
	v_div_scale_f32 v202, s[84:85], v198, v198, v6
	v_div_scale_f32 v203, s[84:85], v199, v199, v7
	v_div_scale_f32 v204, s[84:85], v200, v200, v8
	v_div_scale_f32 v205, s[84:85], v201, v201, v9
	v_rcp_f32_e32 v206, v202
	v_rcp_f32_e32 v207, v203
	v_rcp_f32_e32 v208, v204
	v_rcp_f32_e32 v209, v205
	s_nop 0
	v_div_scale_f32 v210, vcc, v6, v198, v6
	v_fma_f32 v212, -v202, v206, 1.0
	v_fmac_f32_e32 v206, v212, v206
	v_mul_f32_e32 v211, v210, v206
	v_fma_f32 v212, -v202, v211, v210
	v_fmac_f32_e32 v211, v212, v206
	v_fma_f32 v212, -v202, v211, v210
	v_div_fmas_f32 v212, v212, v206, v211
	v_div_fixup_f32 v6, v212, v198, v6
	v_div_scale_f32 v210, vcc, v7, v199, v7
	v_fma_f32 v212, -v203, v207, 1.0
	v_fmac_f32_e32 v207, v212, v207
	v_mul_f32_e32 v211, v210, v207
	v_fma_f32 v212, -v203, v211, v210
	v_fmac_f32_e32 v211, v212, v207
	v_fma_f32 v212, -v203, v211, v210
	v_div_fmas_f32 v212, v212, v207, v211
	v_div_fixup_f32 v7, v212, v199, v7
	v_div_scale_f32 v210, vcc, v8, v200, v8
	v_fma_f32 v212, -v204, v208, 1.0
	v_fmac_f32_e32 v208, v212, v208
	v_mul_f32_e32 v211, v210, v208
	v_fma_f32 v212, -v204, v211, v210
	v_fmac_f32_e32 v211, v212, v208
	v_fma_f32 v212, -v204, v211, v210
	v_div_fmas_f32 v212, v212, v208, v211
	v_div_fixup_f32 v8, v212, v200, v8
	v_div_scale_f32 v210, vcc, v9, v201, v9
	v_fma_f32 v212, -v205, v209, 1.0
	v_fmac_f32_e32 v209, v212, v209
	v_mul_f32_e32 v211, v210, v209
	v_fma_f32 v212, -v205, v211, v210
	v_fmac_f32_e32 v211, v212, v209
	v_fma_f32 v212, -v205, v211, v210
	v_div_fmas_f32 v212, v212, v209, v211
	v_div_fixup_f32 v9, v212, v201, v9
	v_mul_f32_e32 v198, 0xbfb8aa3b, v10
	v_mul_f32_e32 v199, 0xbfb8aa3b, v11
	v_mul_f32_e32 v200, 0xbfb8aa3b, v12
	v_mul_f32_e32 v201, 0xbfb8aa3b, v13
	v_exp_f32_e32 v198, v198
	v_exp_f32_e32 v199, v199
	v_exp_f32_e32 v200, v200
	v_exp_f32_e32 v201, v201
	s_nop 0
	v_add_f32_e32 v198, 1.0, v198
	v_add_f32_e32 v199, 1.0, v199
	v_add_f32_e32 v200, 1.0, v200
	v_add_f32_e32 v201, 1.0, v201
	v_div_scale_f32 v202, s[84:85], v198, v198, v10
	v_div_scale_f32 v203, s[84:85], v199, v199, v11
	v_div_scale_f32 v204, s[84:85], v200, v200, v12
	v_div_scale_f32 v205, s[84:85], v201, v201, v13
	v_rcp_f32_e32 v206, v202
	v_rcp_f32_e32 v207, v203
	v_rcp_f32_e32 v208, v204
	v_rcp_f32_e32 v209, v205
	s_nop 0
	v_div_scale_f32 v210, vcc, v10, v198, v10
	v_fma_f32 v212, -v202, v206, 1.0
	v_fmac_f32_e32 v206, v212, v206
	v_mul_f32_e32 v211, v210, v206
	v_fma_f32 v212, -v202, v211, v210
	v_fmac_f32_e32 v211, v212, v206
	v_fma_f32 v212, -v202, v211, v210
	v_div_fmas_f32 v212, v212, v206, v211
	v_div_fixup_f32 v10, v212, v198, v10
	v_div_scale_f32 v210, vcc, v11, v199, v11
	v_fma_f32 v212, -v203, v207, 1.0
	v_fmac_f32_e32 v207, v212, v207
	v_mul_f32_e32 v211, v210, v207
	v_fma_f32 v212, -v203, v211, v210
	v_fmac_f32_e32 v211, v212, v207
	v_fma_f32 v212, -v203, v211, v210
	v_div_fmas_f32 v212, v212, v207, v211
	v_div_fixup_f32 v11, v212, v199, v11
	v_div_scale_f32 v210, vcc, v12, v200, v12
	v_fma_f32 v212, -v204, v208, 1.0
	v_fmac_f32_e32 v208, v212, v208
	v_mul_f32_e32 v211, v210, v208
	v_fma_f32 v212, -v204, v211, v210
	v_fmac_f32_e32 v211, v212, v208
	v_fma_f32 v212, -v204, v211, v210
	v_div_fmas_f32 v212, v212, v208, v211
	v_div_fixup_f32 v12, v212, v200, v12
	v_div_scale_f32 v210, vcc, v13, v201, v13
	v_fma_f32 v212, -v205, v209, 1.0
	v_fmac_f32_e32 v209, v212, v209
	v_mul_f32_e32 v211, v210, v209
	v_fma_f32 v212, -v205, v211, v210
	v_fmac_f32_e32 v211, v212, v209
	v_fma_f32 v212, -v205, v211, v210
	v_div_fmas_f32 v212, v212, v209, v211
	v_div_fixup_f32 v13, v212, v201, v13
	v_mul_f32_e32 v198, 0xbfb8aa3b, v14
	v_mul_f32_e32 v199, 0xbfb8aa3b, v15
	v_mul_f32_e32 v200, 0xbfb8aa3b, v16
	v_mul_f32_e32 v201, 0xbfb8aa3b, v17
	v_exp_f32_e32 v198, v198
	v_exp_f32_e32 v199, v199
	v_exp_f32_e32 v200, v200
	v_exp_f32_e32 v201, v201
	s_nop 0
	v_add_f32_e32 v198, 1.0, v198
	v_add_f32_e32 v199, 1.0, v199
	v_add_f32_e32 v200, 1.0, v200
	v_add_f32_e32 v201, 1.0, v201
	v_div_scale_f32 v202, s[84:85], v198, v198, v14
	v_div_scale_f32 v203, s[84:85], v199, v199, v15
	v_div_scale_f32 v204, s[84:85], v200, v200, v16
	v_div_scale_f32 v205, s[84:85], v201, v201, v17
	v_rcp_f32_e32 v206, v202
	v_rcp_f32_e32 v207, v203
	v_rcp_f32_e32 v208, v204
	v_rcp_f32_e32 v209, v205
	s_nop 0
	v_div_scale_f32 v210, vcc, v14, v198, v14
	v_fma_f32 v212, -v202, v206, 1.0
	v_fmac_f32_e32 v206, v212, v206
	v_mul_f32_e32 v211, v210, v206
	v_fma_f32 v212, -v202, v211, v210
	v_fmac_f32_e32 v211, v212, v206
	v_fma_f32 v212, -v202, v211, v210
	v_div_fmas_f32 v212, v212, v206, v211
	v_div_fixup_f32 v14, v212, v198, v14
	v_div_scale_f32 v210, vcc, v15, v199, v15
	v_fma_f32 v212, -v203, v207, 1.0
	v_fmac_f32_e32 v207, v212, v207
	v_mul_f32_e32 v211, v210, v207
	v_fma_f32 v212, -v203, v211, v210
	v_fmac_f32_e32 v211, v212, v207
	v_fma_f32 v212, -v203, v211, v210
	v_div_fmas_f32 v212, v212, v207, v211
	v_div_fixup_f32 v15, v212, v199, v15
	v_div_scale_f32 v210, vcc, v16, v200, v16
	v_fma_f32 v212, -v204, v208, 1.0
	v_fmac_f32_e32 v208, v212, v208
	v_mul_f32_e32 v211, v210, v208
	v_fma_f32 v212, -v204, v211, v210
	v_fmac_f32_e32 v211, v212, v208
	v_fma_f32 v212, -v204, v211, v210
	v_div_fmas_f32 v212, v212, v208, v211
	v_div_fixup_f32 v16, v212, v200, v16
	v_div_scale_f32 v210, vcc, v17, v201, v17
	v_fma_f32 v212, -v205, v209, 1.0
	v_fmac_f32_e32 v209, v212, v209
	v_mul_f32_e32 v211, v210, v209
	v_fma_f32 v212, -v205, v211, v210
	v_fmac_f32_e32 v211, v212, v209
	v_fma_f32 v212, -v205, v211, v210
	v_div_fmas_f32 v212, v212, v209, v211
	v_div_fixup_f32 v17, v212, v201, v17
	v_mul_f32_e32 v198, 0xbfb8aa3b, v18
	v_mul_f32_e32 v199, 0xbfb8aa3b, v19
	v_mul_f32_e32 v200, 0xbfb8aa3b, v20
	v_mul_f32_e32 v201, 0xbfb8aa3b, v21
	v_exp_f32_e32 v198, v198
	v_exp_f32_e32 v199, v199
	v_exp_f32_e32 v200, v200
	v_exp_f32_e32 v201, v201
	s_nop 0
	v_add_f32_e32 v198, 1.0, v198
	v_add_f32_e32 v199, 1.0, v199
	v_add_f32_e32 v200, 1.0, v200
	v_add_f32_e32 v201, 1.0, v201
	v_div_scale_f32 v202, s[84:85], v198, v198, v18
	v_div_scale_f32 v203, s[84:85], v199, v199, v19
	v_div_scale_f32 v204, s[84:85], v200, v200, v20
	v_div_scale_f32 v205, s[84:85], v201, v201, v21
	v_rcp_f32_e32 v206, v202
	v_rcp_f32_e32 v207, v203
	v_rcp_f32_e32 v208, v204
	v_rcp_f32_e32 v209, v205
	s_nop 0
	v_div_scale_f32 v210, vcc, v18, v198, v18
	v_fma_f32 v212, -v202, v206, 1.0
	v_fmac_f32_e32 v206, v212, v206
	v_mul_f32_e32 v211, v210, v206
	v_fma_f32 v212, -v202, v211, v210
	v_fmac_f32_e32 v211, v212, v206
	v_fma_f32 v212, -v202, v211, v210
	v_div_fmas_f32 v212, v212, v206, v211
	v_div_fixup_f32 v18, v212, v198, v18
	v_div_scale_f32 v210, vcc, v19, v199, v19
	v_fma_f32 v212, -v203, v207, 1.0
	v_fmac_f32_e32 v207, v212, v207
	v_mul_f32_e32 v211, v210, v207
	v_fma_f32 v212, -v203, v211, v210
	v_fmac_f32_e32 v211, v212, v207
	v_fma_f32 v212, -v203, v211, v210
	v_div_fmas_f32 v212, v212, v207, v211
	v_div_fixup_f32 v19, v212, v199, v19
	v_div_scale_f32 v210, vcc, v20, v200, v20
	v_fma_f32 v212, -v204, v208, 1.0
	v_fmac_f32_e32 v208, v212, v208
	v_mul_f32_e32 v211, v210, v208
	v_fma_f32 v212, -v204, v211, v210
	v_fmac_f32_e32 v211, v212, v208
	v_fma_f32 v212, -v204, v211, v210
	v_div_fmas_f32 v212, v212, v208, v211
	v_div_fixup_f32 v20, v212, v200, v20
	v_div_scale_f32 v210, vcc, v21, v201, v21
	v_fma_f32 v212, -v205, v209, 1.0
	v_fmac_f32_e32 v209, v212, v209
	v_mul_f32_e32 v211, v210, v209
	v_fma_f32 v212, -v205, v211, v210
	v_fmac_f32_e32 v211, v212, v209
	v_fma_f32 v212, -v205, v211, v210
	v_div_fmas_f32 v212, v212, v209, v211
	v_div_fixup_f32 v21, v212, v201, v21
	v_mul_f32_e32 v198, 0xbfb8aa3b, v22
	v_mul_f32_e32 v199, 0xbfb8aa3b, v23
	v_mul_f32_e32 v200, 0xbfb8aa3b, v24
	v_mul_f32_e32 v201, 0xbfb8aa3b, v25
	v_exp_f32_e32 v198, v198
	v_exp_f32_e32 v199, v199
	v_exp_f32_e32 v200, v200
	v_exp_f32_e32 v201, v201
	s_nop 0
	v_add_f32_e32 v198, 1.0, v198
	v_add_f32_e32 v199, 1.0, v199
	v_add_f32_e32 v200, 1.0, v200
	v_add_f32_e32 v201, 1.0, v201
	v_div_scale_f32 v202, s[84:85], v198, v198, v22
	v_div_scale_f32 v203, s[84:85], v199, v199, v23
	v_div_scale_f32 v204, s[84:85], v200, v200, v24
	v_div_scale_f32 v205, s[84:85], v201, v201, v25
	v_rcp_f32_e32 v206, v202
	v_rcp_f32_e32 v207, v203
	v_rcp_f32_e32 v208, v204
	v_rcp_f32_e32 v209, v205
	s_nop 0
	v_div_scale_f32 v210, vcc, v22, v198, v22
	v_fma_f32 v212, -v202, v206, 1.0
	v_fmac_f32_e32 v206, v212, v206
	v_mul_f32_e32 v211, v210, v206
	v_fma_f32 v212, -v202, v211, v210
	v_fmac_f32_e32 v211, v212, v206
	v_fma_f32 v212, -v202, v211, v210
	v_div_fmas_f32 v212, v212, v206, v211
	v_div_fixup_f32 v22, v212, v198, v22
	v_div_scale_f32 v210, vcc, v23, v199, v23
	v_fma_f32 v212, -v203, v207, 1.0
	v_fmac_f32_e32 v207, v212, v207
	v_mul_f32_e32 v211, v210, v207
	v_fma_f32 v212, -v203, v211, v210
	v_fmac_f32_e32 v211, v212, v207
	v_fma_f32 v212, -v203, v211, v210
	v_div_fmas_f32 v212, v212, v207, v211
	v_div_fixup_f32 v23, v212, v199, v23
	v_div_scale_f32 v210, vcc, v24, v200, v24
	v_fma_f32 v212, -v204, v208, 1.0
	v_fmac_f32_e32 v208, v212, v208
	v_mul_f32_e32 v211, v210, v208
	v_fma_f32 v212, -v204, v211, v210
	v_fmac_f32_e32 v211, v212, v208
	v_fma_f32 v212, -v204, v211, v210
	v_div_fmas_f32 v212, v212, v208, v211
	v_div_fixup_f32 v24, v212, v200, v24
	v_div_scale_f32 v210, vcc, v25, v201, v25
	v_fma_f32 v212, -v205, v209, 1.0
	v_fmac_f32_e32 v209, v212, v209
	v_mul_f32_e32 v211, v210, v209
	v_fma_f32 v212, -v205, v211, v210
	v_fmac_f32_e32 v211, v212, v209
	v_fma_f32 v212, -v205, v211, v210
	v_div_fmas_f32 v212, v212, v209, v211
	v_div_fixup_f32 v25, v212, v201, v25
	v_mul_f32_e32 v198, 0xbfb8aa3b, v26
	v_mul_f32_e32 v199, 0xbfb8aa3b, v27
	v_mul_f32_e32 v200, 0xbfb8aa3b, v28
	v_mul_f32_e32 v201, 0xbfb8aa3b, v29
	v_exp_f32_e32 v198, v198
	v_exp_f32_e32 v199, v199
	v_exp_f32_e32 v200, v200
	v_exp_f32_e32 v201, v201
	s_nop 0
	v_add_f32_e32 v198, 1.0, v198
	v_add_f32_e32 v199, 1.0, v199
	v_add_f32_e32 v200, 1.0, v200
	v_add_f32_e32 v201, 1.0, v201
	v_div_scale_f32 v202, s[84:85], v198, v198, v26
	v_div_scale_f32 v203, s[84:85], v199, v199, v27
	v_div_scale_f32 v204, s[84:85], v200, v200, v28
	v_div_scale_f32 v205, s[84:85], v201, v201, v29
	v_rcp_f32_e32 v206, v202
	v_rcp_f32_e32 v207, v203
	v_rcp_f32_e32 v208, v204
	v_rcp_f32_e32 v209, v205
	s_nop 0
	v_div_scale_f32 v210, vcc, v26, v198, v26
	v_fma_f32 v212, -v202, v206, 1.0
	v_fmac_f32_e32 v206, v212, v206
	v_mul_f32_e32 v211, v210, v206
	v_fma_f32 v212, -v202, v211, v210
	v_fmac_f32_e32 v211, v212, v206
	v_fma_f32 v212, -v202, v211, v210
	v_div_fmas_f32 v212, v212, v206, v211
	v_div_fixup_f32 v26, v212, v198, v26
	v_div_scale_f32 v210, vcc, v27, v199, v27
	v_fma_f32 v212, -v203, v207, 1.0
	v_fmac_f32_e32 v207, v212, v207
	v_mul_f32_e32 v211, v210, v207
	v_fma_f32 v212, -v203, v211, v210
	v_fmac_f32_e32 v211, v212, v207
	v_fma_f32 v212, -v203, v211, v210
	v_div_fmas_f32 v212, v212, v207, v211
	v_div_fixup_f32 v27, v212, v199, v27
	v_div_scale_f32 v210, vcc, v28, v200, v28
	v_fma_f32 v212, -v204, v208, 1.0
	v_fmac_f32_e32 v208, v212, v208
	v_mul_f32_e32 v211, v210, v208
	v_fma_f32 v212, -v204, v211, v210
	v_fmac_f32_e32 v211, v212, v208
	v_fma_f32 v212, -v204, v211, v210
	v_div_fmas_f32 v212, v212, v208, v211
	v_div_fixup_f32 v28, v212, v200, v28
	v_div_scale_f32 v210, vcc, v29, v201, v29
	v_fma_f32 v212, -v205, v209, 1.0
	v_fmac_f32_e32 v209, v212, v209
	v_mul_f32_e32 v211, v210, v209
	v_fma_f32 v212, -v205, v211, v210
	v_fmac_f32_e32 v211, v212, v209
	v_fma_f32 v212, -v205, v211, v210
	v_div_fmas_f32 v212, v212, v209, v211
	v_div_fixup_f32 v29, v212, v201, v29
	v_mul_f32_e32 v198, 0xbfb8aa3b, v30
	v_mul_f32_e32 v199, 0xbfb8aa3b, v31
	v_mul_f32_e32 v200, 0xbfb8aa3b, v32
	v_mul_f32_e32 v201, 0xbfb8aa3b, v33
	v_exp_f32_e32 v198, v198
	v_exp_f32_e32 v199, v199
	v_exp_f32_e32 v200, v200
	v_exp_f32_e32 v201, v201
	s_nop 0
	v_add_f32_e32 v198, 1.0, v198
	v_add_f32_e32 v199, 1.0, v199
	v_add_f32_e32 v200, 1.0, v200
	v_add_f32_e32 v201, 1.0, v201
	v_div_scale_f32 v202, s[84:85], v198, v198, v30
	v_div_scale_f32 v203, s[84:85], v199, v199, v31
	v_div_scale_f32 v204, s[84:85], v200, v200, v32
	v_div_scale_f32 v205, s[84:85], v201, v201, v33
	v_rcp_f32_e32 v206, v202
	v_rcp_f32_e32 v207, v203
	v_rcp_f32_e32 v208, v204
	v_rcp_f32_e32 v209, v205
	s_nop 0
	v_div_scale_f32 v210, vcc, v30, v198, v30
	v_fma_f32 v212, -v202, v206, 1.0
	v_fmac_f32_e32 v206, v212, v206
	v_mul_f32_e32 v211, v210, v206
	v_fma_f32 v212, -v202, v211, v210
	v_fmac_f32_e32 v211, v212, v206
	v_fma_f32 v212, -v202, v211, v210
	v_div_fmas_f32 v212, v212, v206, v211
	v_div_fixup_f32 v30, v212, v198, v30
	v_div_scale_f32 v210, vcc, v31, v199, v31
	v_fma_f32 v212, -v203, v207, 1.0
	v_fmac_f32_e32 v207, v212, v207
	v_mul_f32_e32 v211, v210, v207
	v_fma_f32 v212, -v203, v211, v210
	v_fmac_f32_e32 v211, v212, v207
	v_fma_f32 v212, -v203, v211, v210
	v_div_fmas_f32 v212, v212, v207, v211
	v_div_fixup_f32 v31, v212, v199, v31
	v_div_scale_f32 v210, vcc, v32, v200, v32
	v_fma_f32 v212, -v204, v208, 1.0
	v_fmac_f32_e32 v208, v212, v208
	v_mul_f32_e32 v211, v210, v208
	v_fma_f32 v212, -v204, v211, v210
	v_fmac_f32_e32 v211, v212, v208
	v_fma_f32 v212, -v204, v211, v210
	v_div_fmas_f32 v212, v212, v208, v211
	v_div_fixup_f32 v32, v212, v200, v32
	v_div_scale_f32 v210, vcc, v33, v201, v33
	v_fma_f32 v212, -v205, v209, 1.0
	v_fmac_f32_e32 v209, v212, v209
	v_mul_f32_e32 v211, v210, v209
	v_fma_f32 v212, -v205, v211, v210
	v_fmac_f32_e32 v211, v212, v209
	v_fma_f32 v212, -v205, v211, v210
	v_div_fmas_f32 v212, v212, v209, v211
	v_div_fixup_f32 v33, v212, v201, v33
	v_mul_f32_e32 v198, 0xbfb8aa3b, v34
	v_mul_f32_e32 v199, 0xbfb8aa3b, v35
	v_mul_f32_e32 v200, 0xbfb8aa3b, v36
	v_mul_f32_e32 v201, 0xbfb8aa3b, v37
	v_exp_f32_e32 v198, v198
	v_exp_f32_e32 v199, v199
	v_exp_f32_e32 v200, v200
	v_exp_f32_e32 v201, v201
	s_nop 0
	v_add_f32_e32 v198, 1.0, v198
	v_add_f32_e32 v199, 1.0, v199
	v_add_f32_e32 v200, 1.0, v200
	v_add_f32_e32 v201, 1.0, v201
	v_div_scale_f32 v202, s[84:85], v198, v198, v34
	v_div_scale_f32 v203, s[84:85], v199, v199, v35
	v_div_scale_f32 v204, s[84:85], v200, v200, v36
	v_div_scale_f32 v205, s[84:85], v201, v201, v37
	v_rcp_f32_e32 v206, v202
	v_rcp_f32_e32 v207, v203
	v_rcp_f32_e32 v208, v204
	v_rcp_f32_e32 v209, v205
	s_nop 0
	v_div_scale_f32 v210, vcc, v34, v198, v34
	v_fma_f32 v212, -v202, v206, 1.0
	v_fmac_f32_e32 v206, v212, v206
	v_mul_f32_e32 v211, v210, v206
	v_fma_f32 v212, -v202, v211, v210
	v_fmac_f32_e32 v211, v212, v206
	v_fma_f32 v212, -v202, v211, v210
	v_div_fmas_f32 v212, v212, v206, v211
	v_div_fixup_f32 v34, v212, v198, v34
	v_div_scale_f32 v210, vcc, v35, v199, v35
	v_fma_f32 v212, -v203, v207, 1.0
	v_fmac_f32_e32 v207, v212, v207
	v_mul_f32_e32 v211, v210, v207
	v_fma_f32 v212, -v203, v211, v210
	v_fmac_f32_e32 v211, v212, v207
	v_fma_f32 v212, -v203, v211, v210
	v_div_fmas_f32 v212, v212, v207, v211
	v_div_fixup_f32 v35, v212, v199, v35
	v_div_scale_f32 v210, vcc, v36, v200, v36
	v_fma_f32 v212, -v204, v208, 1.0
	v_fmac_f32_e32 v208, v212, v208
	v_mul_f32_e32 v211, v210, v208
	v_fma_f32 v212, -v204, v211, v210
	v_fmac_f32_e32 v211, v212, v208
	v_fma_f32 v212, -v204, v211, v210
	v_div_fmas_f32 v212, v212, v208, v211
	v_div_fixup_f32 v36, v212, v200, v36
	v_div_scale_f32 v210, vcc, v37, v201, v37
	v_fma_f32 v212, -v205, v209, 1.0
	v_fmac_f32_e32 v209, v212, v209
	v_mul_f32_e32 v211, v210, v209
	v_fma_f32 v212, -v205, v211, v210
	v_fmac_f32_e32 v211, v212, v209
	v_fma_f32 v212, -v205, v211, v210
	v_div_fmas_f32 v212, v212, v209, v211
	v_div_fixup_f32 v37, v212, v201, v37
	v_mul_f32_e32 v198, 0xbfb8aa3b, v38
	v_mul_f32_e32 v199, 0xbfb8aa3b, v39
	v_mul_f32_e32 v200, 0xbfb8aa3b, v40
	v_mul_f32_e32 v201, 0xbfb8aa3b, v41
	v_exp_f32_e32 v198, v198
	v_exp_f32_e32 v199, v199
	v_exp_f32_e32 v200, v200
	v_exp_f32_e32 v201, v201
	s_nop 0
	v_add_f32_e32 v198, 1.0, v198
	v_add_f32_e32 v199, 1.0, v199
	v_add_f32_e32 v200, 1.0, v200
	v_add_f32_e32 v201, 1.0, v201
	v_div_scale_f32 v202, s[84:85], v198, v198, v38
	v_div_scale_f32 v203, s[84:85], v199, v199, v39
	v_div_scale_f32 v204, s[84:85], v200, v200, v40
	v_div_scale_f32 v205, s[84:85], v201, v201, v41
	v_rcp_f32_e32 v206, v202
	v_rcp_f32_e32 v207, v203
	v_rcp_f32_e32 v208, v204
	v_rcp_f32_e32 v209, v205
	s_nop 0
	v_div_scale_f32 v210, vcc, v38, v198, v38
	v_fma_f32 v212, -v202, v206, 1.0
	v_fmac_f32_e32 v206, v212, v206
	v_mul_f32_e32 v211, v210, v206
	v_fma_f32 v212, -v202, v211, v210
	v_fmac_f32_e32 v211, v212, v206
	v_fma_f32 v212, -v202, v211, v210
	v_div_fmas_f32 v212, v212, v206, v211
	v_div_fixup_f32 v38, v212, v198, v38
	v_div_scale_f32 v210, vcc, v39, v199, v39
	v_fma_f32 v212, -v203, v207, 1.0
	v_fmac_f32_e32 v207, v212, v207
	v_mul_f32_e32 v211, v210, v207
	v_fma_f32 v212, -v203, v211, v210
	v_fmac_f32_e32 v211, v212, v207
	v_fma_f32 v212, -v203, v211, v210
	v_div_fmas_f32 v212, v212, v207, v211
	v_div_fixup_f32 v39, v212, v199, v39
	v_div_scale_f32 v210, vcc, v40, v200, v40
	v_fma_f32 v212, -v204, v208, 1.0
	v_fmac_f32_e32 v208, v212, v208
	v_mul_f32_e32 v211, v210, v208
	v_fma_f32 v212, -v204, v211, v210
	v_fmac_f32_e32 v211, v212, v208
	v_fma_f32 v212, -v204, v211, v210
	v_div_fmas_f32 v212, v212, v208, v211
	v_div_fixup_f32 v40, v212, v200, v40
	v_div_scale_f32 v210, vcc, v41, v201, v41
	v_fma_f32 v212, -v205, v209, 1.0
	v_fmac_f32_e32 v209, v212, v209
	v_mul_f32_e32 v211, v210, v209
	v_fma_f32 v212, -v205, v211, v210
	v_fmac_f32_e32 v211, v212, v209
	v_fma_f32 v212, -v205, v211, v210
	v_div_fmas_f32 v212, v212, v209, v211
	v_div_fixup_f32 v41, v212, v201, v41
	v_mul_f32_e32 v198, 0xbfb8aa3b, v42
	v_mul_f32_e32 v199, 0xbfb8aa3b, v43
	v_mul_f32_e32 v200, 0xbfb8aa3b, v44
	v_mul_f32_e32 v201, 0xbfb8aa3b, v45
	v_exp_f32_e32 v198, v198
	v_exp_f32_e32 v199, v199
	v_exp_f32_e32 v200, v200
	v_exp_f32_e32 v201, v201
	s_nop 0
	v_add_f32_e32 v198, 1.0, v198
	v_add_f32_e32 v199, 1.0, v199
	v_add_f32_e32 v200, 1.0, v200
	v_add_f32_e32 v201, 1.0, v201
	v_div_scale_f32 v202, s[84:85], v198, v198, v42
	v_div_scale_f32 v203, s[84:85], v199, v199, v43
	v_div_scale_f32 v204, s[84:85], v200, v200, v44
	v_div_scale_f32 v205, s[84:85], v201, v201, v45
	v_rcp_f32_e32 v206, v202
	v_rcp_f32_e32 v207, v203
	v_rcp_f32_e32 v208, v204
	v_rcp_f32_e32 v209, v205
	s_nop 0
	v_div_scale_f32 v210, vcc, v42, v198, v42
	v_fma_f32 v212, -v202, v206, 1.0
	v_fmac_f32_e32 v206, v212, v206
	v_mul_f32_e32 v211, v210, v206
	v_fma_f32 v212, -v202, v211, v210
	v_fmac_f32_e32 v211, v212, v206
	v_fma_f32 v212, -v202, v211, v210
	v_div_fmas_f32 v212, v212, v206, v211
	v_div_fixup_f32 v42, v212, v198, v42
	v_div_scale_f32 v210, vcc, v43, v199, v43
	v_fma_f32 v212, -v203, v207, 1.0
	v_fmac_f32_e32 v207, v212, v207
	v_mul_f32_e32 v211, v210, v207
	v_fma_f32 v212, -v203, v211, v210
	v_fmac_f32_e32 v211, v212, v207
	v_fma_f32 v212, -v203, v211, v210
	v_div_fmas_f32 v212, v212, v207, v211
	v_div_fixup_f32 v43, v212, v199, v43
	v_div_scale_f32 v210, vcc, v44, v200, v44
	v_fma_f32 v212, -v204, v208, 1.0
	v_fmac_f32_e32 v208, v212, v208
	v_mul_f32_e32 v211, v210, v208
	v_fma_f32 v212, -v204, v211, v210
	v_fmac_f32_e32 v211, v212, v208
	v_fma_f32 v212, -v204, v211, v210
	v_div_fmas_f32 v212, v212, v208, v211
	v_div_fixup_f32 v44, v212, v200, v44
	v_div_scale_f32 v210, vcc, v45, v201, v45
	v_fma_f32 v212, -v205, v209, 1.0
	v_fmac_f32_e32 v209, v212, v209
	v_mul_f32_e32 v211, v210, v209
	v_fma_f32 v212, -v205, v211, v210
	v_fmac_f32_e32 v211, v212, v209
	v_fma_f32 v212, -v205, v211, v210
	v_div_fmas_f32 v212, v212, v209, v211
	v_div_fixup_f32 v45, v212, v201, v45
	v_mul_f32_e32 v198, 0xbfb8aa3b, v46
	v_mul_f32_e32 v199, 0xbfb8aa3b, v47
	v_mul_f32_e32 v200, 0xbfb8aa3b, v48
	v_mul_f32_e32 v201, 0xbfb8aa3b, v49
	v_exp_f32_e32 v198, v198
	v_exp_f32_e32 v199, v199
	v_exp_f32_e32 v200, v200
	v_exp_f32_e32 v201, v201
	s_nop 0
	v_add_f32_e32 v198, 1.0, v198
	v_add_f32_e32 v199, 1.0, v199
	v_add_f32_e32 v200, 1.0, v200
	v_add_f32_e32 v201, 1.0, v201
	v_div_scale_f32 v202, s[84:85], v198, v198, v46
	v_div_scale_f32 v203, s[84:85], v199, v199, v47
	v_div_scale_f32 v204, s[84:85], v200, v200, v48
	v_div_scale_f32 v205, s[84:85], v201, v201, v49
	v_rcp_f32_e32 v206, v202
	v_rcp_f32_e32 v207, v203
	v_rcp_f32_e32 v208, v204
	v_rcp_f32_e32 v209, v205
	s_nop 0
	v_div_scale_f32 v210, vcc, v46, v198, v46
	v_fma_f32 v212, -v202, v206, 1.0
	v_fmac_f32_e32 v206, v212, v206
	v_mul_f32_e32 v211, v210, v206
	v_fma_f32 v212, -v202, v211, v210
	v_fmac_f32_e32 v211, v212, v206
	v_fma_f32 v212, -v202, v211, v210
	v_div_fmas_f32 v212, v212, v206, v211
	v_div_fixup_f32 v46, v212, v198, v46
	v_div_scale_f32 v210, vcc, v47, v199, v47
	v_fma_f32 v212, -v203, v207, 1.0
	v_fmac_f32_e32 v207, v212, v207
	v_mul_f32_e32 v211, v210, v207
	v_fma_f32 v212, -v203, v211, v210
	v_fmac_f32_e32 v211, v212, v207
	v_fma_f32 v212, -v203, v211, v210
	v_div_fmas_f32 v212, v212, v207, v211
	v_div_fixup_f32 v47, v212, v199, v47
	v_div_scale_f32 v210, vcc, v48, v200, v48
	v_fma_f32 v212, -v204, v208, 1.0
	v_fmac_f32_e32 v208, v212, v208
	v_mul_f32_e32 v211, v210, v208
	v_fma_f32 v212, -v204, v211, v210
	v_fmac_f32_e32 v211, v212, v208
	v_fma_f32 v212, -v204, v211, v210
	v_div_fmas_f32 v212, v212, v208, v211
	v_div_fixup_f32 v48, v212, v200, v48
	v_div_scale_f32 v210, vcc, v49, v201, v49
	v_fma_f32 v212, -v205, v209, 1.0
	v_fmac_f32_e32 v209, v212, v209
	v_mul_f32_e32 v211, v210, v209
	v_fma_f32 v212, -v205, v211, v210
	v_fmac_f32_e32 v211, v212, v209
	v_fma_f32 v212, -v205, v211, v210
	v_div_fmas_f32 v212, v212, v209, v211
	v_div_fixup_f32 v49, v212, v201, v49
	v_mul_f32_e32 v198, 0xbfb8aa3b, v50
	v_mul_f32_e32 v199, 0xbfb8aa3b, v51
	v_mul_f32_e32 v200, 0xbfb8aa3b, v52
	v_mul_f32_e32 v201, 0xbfb8aa3b, v53
	v_exp_f32_e32 v198, v198
	v_exp_f32_e32 v199, v199
	v_exp_f32_e32 v200, v200
	v_exp_f32_e32 v201, v201
	s_nop 0
	v_add_f32_e32 v198, 1.0, v198
	v_add_f32_e32 v199, 1.0, v199
	v_add_f32_e32 v200, 1.0, v200
	v_add_f32_e32 v201, 1.0, v201
	v_div_scale_f32 v202, s[84:85], v198, v198, v50
	v_div_scale_f32 v203, s[84:85], v199, v199, v51
	v_div_scale_f32 v204, s[84:85], v200, v200, v52
	v_div_scale_f32 v205, s[84:85], v201, v201, v53
	v_rcp_f32_e32 v206, v202
	v_rcp_f32_e32 v207, v203
	v_rcp_f32_e32 v208, v204
	v_rcp_f32_e32 v209, v205
	s_nop 0
	v_div_scale_f32 v210, vcc, v50, v198, v50
	v_fma_f32 v212, -v202, v206, 1.0
	v_fmac_f32_e32 v206, v212, v206
	v_mul_f32_e32 v211, v210, v206
	v_fma_f32 v212, -v202, v211, v210
	v_fmac_f32_e32 v211, v212, v206
	v_fma_f32 v212, -v202, v211, v210
	v_div_fmas_f32 v212, v212, v206, v211
	v_div_fixup_f32 v50, v212, v198, v50
	v_div_scale_f32 v210, vcc, v51, v199, v51
	v_fma_f32 v212, -v203, v207, 1.0
	v_fmac_f32_e32 v207, v212, v207
	v_mul_f32_e32 v211, v210, v207
	v_fma_f32 v212, -v203, v211, v210
	v_fmac_f32_e32 v211, v212, v207
	v_fma_f32 v212, -v203, v211, v210
	v_div_fmas_f32 v212, v212, v207, v211
	v_div_fixup_f32 v51, v212, v199, v51
	v_div_scale_f32 v210, vcc, v52, v200, v52
	v_fma_f32 v212, -v204, v208, 1.0
	v_fmac_f32_e32 v208, v212, v208
	v_mul_f32_e32 v211, v210, v208
	v_fma_f32 v212, -v204, v211, v210
	v_fmac_f32_e32 v211, v212, v208
	v_fma_f32 v212, -v204, v211, v210
	v_div_fmas_f32 v212, v212, v208, v211
	v_div_fixup_f32 v52, v212, v200, v52
	v_div_scale_f32 v210, vcc, v53, v201, v53
	v_fma_f32 v212, -v205, v209, 1.0
	v_fmac_f32_e32 v209, v212, v209
	v_mul_f32_e32 v211, v210, v209
	v_fma_f32 v212, -v205, v211, v210
	v_fmac_f32_e32 v211, v212, v209
	v_fma_f32 v212, -v205, v211, v210
	v_div_fmas_f32 v212, v212, v209, v211
	v_div_fixup_f32 v53, v212, v201, v53
	v_mul_f32_e32 v198, 0xbfb8aa3b, v54
	v_mul_f32_e32 v199, 0xbfb8aa3b, v55
	v_mul_f32_e32 v200, 0xbfb8aa3b, v56
	v_mul_f32_e32 v201, 0xbfb8aa3b, v57
	v_exp_f32_e32 v198, v198
	v_exp_f32_e32 v199, v199
	v_exp_f32_e32 v200, v200
	v_exp_f32_e32 v201, v201
	s_nop 0
	v_add_f32_e32 v198, 1.0, v198
	v_add_f32_e32 v199, 1.0, v199
	v_add_f32_e32 v200, 1.0, v200
	v_add_f32_e32 v201, 1.0, v201
	v_div_scale_f32 v202, s[84:85], v198, v198, v54
	v_div_scale_f32 v203, s[84:85], v199, v199, v55
	v_div_scale_f32 v204, s[84:85], v200, v200, v56
	v_div_scale_f32 v205, s[84:85], v201, v201, v57
	v_rcp_f32_e32 v206, v202
	v_rcp_f32_e32 v207, v203
	v_rcp_f32_e32 v208, v204
	v_rcp_f32_e32 v209, v205
	s_nop 0
	v_div_scale_f32 v210, vcc, v54, v198, v54
	v_fma_f32 v212, -v202, v206, 1.0
	v_fmac_f32_e32 v206, v212, v206
	v_mul_f32_e32 v211, v210, v206
	v_fma_f32 v212, -v202, v211, v210
	v_fmac_f32_e32 v211, v212, v206
	v_fma_f32 v212, -v202, v211, v210
	v_div_fmas_f32 v212, v212, v206, v211
	v_div_fixup_f32 v54, v212, v198, v54
	v_div_scale_f32 v210, vcc, v55, v199, v55
	v_fma_f32 v212, -v203, v207, 1.0
	v_fmac_f32_e32 v207, v212, v207
	v_mul_f32_e32 v211, v210, v207
	v_fma_f32 v212, -v203, v211, v210
	v_fmac_f32_e32 v211, v212, v207
	v_fma_f32 v212, -v203, v211, v210
	v_div_fmas_f32 v212, v212, v207, v211
	v_div_fixup_f32 v55, v212, v199, v55
	v_div_scale_f32 v210, vcc, v56, v200, v56
	v_fma_f32 v212, -v204, v208, 1.0
	v_fmac_f32_e32 v208, v212, v208
	v_mul_f32_e32 v211, v210, v208
	v_fma_f32 v212, -v204, v211, v210
	v_fmac_f32_e32 v211, v212, v208
	v_fma_f32 v212, -v204, v211, v210
	v_div_fmas_f32 v212, v212, v208, v211
	v_div_fixup_f32 v56, v212, v200, v56
	v_div_scale_f32 v210, vcc, v57, v201, v57
	v_fma_f32 v212, -v205, v209, 1.0
	v_fmac_f32_e32 v209, v212, v209
	v_mul_f32_e32 v211, v210, v209
	v_fma_f32 v212, -v205, v211, v210
	v_fmac_f32_e32 v211, v212, v209
	v_fma_f32 v212, -v205, v211, v210
	v_div_fmas_f32 v212, v212, v209, v211
	v_div_fixup_f32 v57, v212, v201, v57
	v_mul_f32_e32 v198, 0xbfb8aa3b, v58
	v_mul_f32_e32 v199, 0xbfb8aa3b, v59
	v_mul_f32_e32 v200, 0xbfb8aa3b, v60
	v_mul_f32_e32 v201, 0xbfb8aa3b, v61
	v_exp_f32_e32 v198, v198
	v_exp_f32_e32 v199, v199
	v_exp_f32_e32 v200, v200
	v_exp_f32_e32 v201, v201
	s_nop 0
	v_add_f32_e32 v198, 1.0, v198
	v_add_f32_e32 v199, 1.0, v199
	v_add_f32_e32 v200, 1.0, v200
	v_add_f32_e32 v201, 1.0, v201
	v_div_scale_f32 v202, s[84:85], v198, v198, v58
	v_div_scale_f32 v203, s[84:85], v199, v199, v59
	v_div_scale_f32 v204, s[84:85], v200, v200, v60
	v_div_scale_f32 v205, s[84:85], v201, v201, v61
	v_rcp_f32_e32 v206, v202
	v_rcp_f32_e32 v207, v203
	v_rcp_f32_e32 v208, v204
	v_rcp_f32_e32 v209, v205
	s_nop 0
	v_div_scale_f32 v210, vcc, v58, v198, v58
	v_fma_f32 v212, -v202, v206, 1.0
	v_fmac_f32_e32 v206, v212, v206
	v_mul_f32_e32 v211, v210, v206
	v_fma_f32 v212, -v202, v211, v210
	v_fmac_f32_e32 v211, v212, v206
	v_fma_f32 v212, -v202, v211, v210
	v_div_fmas_f32 v212, v212, v206, v211
	v_div_fixup_f32 v58, v212, v198, v58
	v_div_scale_f32 v210, vcc, v59, v199, v59
	v_fma_f32 v212, -v203, v207, 1.0
	v_fmac_f32_e32 v207, v212, v207
	v_mul_f32_e32 v211, v210, v207
	v_fma_f32 v212, -v203, v211, v210
	v_fmac_f32_e32 v211, v212, v207
	v_fma_f32 v212, -v203, v211, v210
	v_div_fmas_f32 v212, v212, v207, v211
	v_div_fixup_f32 v59, v212, v199, v59
	v_div_scale_f32 v210, vcc, v60, v200, v60
	v_fma_f32 v212, -v204, v208, 1.0
	v_fmac_f32_e32 v208, v212, v208
	v_mul_f32_e32 v211, v210, v208
	v_fma_f32 v212, -v204, v211, v210
	v_fmac_f32_e32 v211, v212, v208
	v_fma_f32 v212, -v204, v211, v210
	v_div_fmas_f32 v212, v212, v208, v211
	v_div_fixup_f32 v60, v212, v200, v60
	v_div_scale_f32 v210, vcc, v61, v201, v61
	v_fma_f32 v212, -v205, v209, 1.0
	v_fmac_f32_e32 v209, v212, v209
	v_mul_f32_e32 v211, v210, v209
	v_fma_f32 v212, -v205, v211, v210
	v_fmac_f32_e32 v211, v212, v209
	v_fma_f32 v212, -v205, v211, v210
	v_div_fmas_f32 v212, v212, v209, v211
	v_div_fixup_f32 v61, v212, v201, v61
	v_mul_f32_e32 v198, 0xbfb8aa3b, v62
	v_mul_f32_e32 v199, 0xbfb8aa3b, v63
	v_mul_f32_e32 v200, 0xbfb8aa3b, v64
	v_mul_f32_e32 v201, 0xbfb8aa3b, v65
	v_exp_f32_e32 v198, v198
	v_exp_f32_e32 v199, v199
	v_exp_f32_e32 v200, v200
	v_exp_f32_e32 v201, v201
	s_nop 0
	v_add_f32_e32 v198, 1.0, v198
	v_add_f32_e32 v199, 1.0, v199
	v_add_f32_e32 v200, 1.0, v200
	v_add_f32_e32 v201, 1.0, v201
	v_div_scale_f32 v202, s[84:85], v198, v198, v62
	v_div_scale_f32 v203, s[84:85], v199, v199, v63
	v_div_scale_f32 v204, s[84:85], v200, v200, v64
	v_div_scale_f32 v205, s[84:85], v201, v201, v65
	v_rcp_f32_e32 v206, v202
	v_rcp_f32_e32 v207, v203
	v_rcp_f32_e32 v208, v204
	v_rcp_f32_e32 v209, v205
	s_nop 0
	v_div_scale_f32 v210, vcc, v62, v198, v62
	v_fma_f32 v212, -v202, v206, 1.0
	v_fmac_f32_e32 v206, v212, v206
	v_mul_f32_e32 v211, v210, v206
	v_fma_f32 v212, -v202, v211, v210
	v_fmac_f32_e32 v211, v212, v206
	v_fma_f32 v212, -v202, v211, v210
	v_div_fmas_f32 v212, v212, v206, v211
	v_div_fixup_f32 v62, v212, v198, v62
	v_div_scale_f32 v210, vcc, v63, v199, v63
	v_fma_f32 v212, -v203, v207, 1.0
	v_fmac_f32_e32 v207, v212, v207
	v_mul_f32_e32 v211, v210, v207
	v_fma_f32 v212, -v203, v211, v210
	v_fmac_f32_e32 v211, v212, v207
	v_fma_f32 v212, -v203, v211, v210
	v_div_fmas_f32 v212, v212, v207, v211
	v_div_fixup_f32 v63, v212, v199, v63
	v_div_scale_f32 v210, vcc, v64, v200, v64
	v_fma_f32 v212, -v204, v208, 1.0
	v_fmac_f32_e32 v208, v212, v208
	v_mul_f32_e32 v211, v210, v208
	v_fma_f32 v212, -v204, v211, v210
	v_fmac_f32_e32 v211, v212, v208
	v_fma_f32 v212, -v204, v211, v210
	v_div_fmas_f32 v212, v212, v208, v211
	v_div_fixup_f32 v64, v212, v200, v64
	v_div_scale_f32 v210, vcc, v65, v201, v65
	v_fma_f32 v212, -v205, v209, 1.0
	v_fmac_f32_e32 v209, v212, v209
	v_mul_f32_e32 v211, v210, v209
	v_fma_f32 v212, -v205, v211, v210
	v_fmac_f32_e32 v211, v212, v209
	v_fma_f32 v212, -v205, v211, v210
	v_div_fmas_f32 v212, v212, v209, v211
	v_div_fixup_f32 v65, v212, v201, v65
	v_mul_f32_e32 v198, 0xbfb8aa3b, v66
	v_mul_f32_e32 v199, 0xbfb8aa3b, v67
	v_mul_f32_e32 v200, 0xbfb8aa3b, v68
	v_mul_f32_e32 v201, 0xbfb8aa3b, v69
	v_exp_f32_e32 v198, v198
	v_exp_f32_e32 v199, v199
	v_exp_f32_e32 v200, v200
	v_exp_f32_e32 v201, v201
	s_nop 0
	v_add_f32_e32 v198, 1.0, v198
	v_add_f32_e32 v199, 1.0, v199
	v_add_f32_e32 v200, 1.0, v200
	v_add_f32_e32 v201, 1.0, v201
	v_div_scale_f32 v202, s[84:85], v198, v198, v66
	v_div_scale_f32 v203, s[84:85], v199, v199, v67
	v_div_scale_f32 v204, s[84:85], v200, v200, v68
	v_div_scale_f32 v205, s[84:85], v201, v201, v69
	v_rcp_f32_e32 v206, v202
	v_rcp_f32_e32 v207, v203
	v_rcp_f32_e32 v208, v204
	v_rcp_f32_e32 v209, v205
	s_nop 0
	v_div_scale_f32 v210, vcc, v66, v198, v66
	v_fma_f32 v212, -v202, v206, 1.0
	v_fmac_f32_e32 v206, v212, v206
	v_mul_f32_e32 v211, v210, v206
	v_fma_f32 v212, -v202, v211, v210
	v_fmac_f32_e32 v211, v212, v206
	v_fma_f32 v212, -v202, v211, v210
	v_div_fmas_f32 v212, v212, v206, v211
	v_div_fixup_f32 v66, v212, v198, v66
	v_div_scale_f32 v210, vcc, v67, v199, v67
	v_fma_f32 v212, -v203, v207, 1.0
	v_fmac_f32_e32 v207, v212, v207
	v_mul_f32_e32 v211, v210, v207
	v_fma_f32 v212, -v203, v211, v210
	v_fmac_f32_e32 v211, v212, v207
	v_fma_f32 v212, -v203, v211, v210
	v_div_fmas_f32 v212, v212, v207, v211
	v_div_fixup_f32 v67, v212, v199, v67
	v_div_scale_f32 v210, vcc, v68, v200, v68
	v_fma_f32 v212, -v204, v208, 1.0
	v_fmac_f32_e32 v208, v212, v208
	v_mul_f32_e32 v211, v210, v208
	v_fma_f32 v212, -v204, v211, v210
	v_fmac_f32_e32 v211, v212, v208
	v_fma_f32 v212, -v204, v211, v210
	v_div_fmas_f32 v212, v212, v208, v211
	v_div_fixup_f32 v68, v212, v200, v68
	v_div_scale_f32 v210, vcc, v69, v201, v69
	v_fma_f32 v212, -v205, v209, 1.0
	v_fmac_f32_e32 v209, v212, v209
	v_mul_f32_e32 v211, v210, v209
	v_fma_f32 v212, -v205, v211, v210
	v_fmac_f32_e32 v211, v212, v209
	v_fma_f32 v212, -v205, v211, v210
	v_div_fmas_f32 v212, v212, v209, v211
	v_div_fixup_f32 v69, v212, v201, v69
	v_mul_f32_e32 v198, 0xbfb8aa3b, v70
	v_mul_f32_e32 v199, 0xbfb8aa3b, v71
	v_mul_f32_e32 v200, 0xbfb8aa3b, v72
	v_mul_f32_e32 v201, 0xbfb8aa3b, v73
	v_exp_f32_e32 v198, v198
	v_exp_f32_e32 v199, v199
	v_exp_f32_e32 v200, v200
	v_exp_f32_e32 v201, v201
	s_nop 0
	v_add_f32_e32 v198, 1.0, v198
	v_add_f32_e32 v199, 1.0, v199
	v_add_f32_e32 v200, 1.0, v200
	v_add_f32_e32 v201, 1.0, v201
	v_div_scale_f32 v202, s[84:85], v198, v198, v70
	v_div_scale_f32 v203, s[84:85], v199, v199, v71
	v_div_scale_f32 v204, s[84:85], v200, v200, v72
	v_div_scale_f32 v205, s[84:85], v201, v201, v73
	v_rcp_f32_e32 v206, v202
	v_rcp_f32_e32 v207, v203
	v_rcp_f32_e32 v208, v204
	v_rcp_f32_e32 v209, v205
	s_nop 0
	v_div_scale_f32 v210, vcc, v70, v198, v70
	v_fma_f32 v212, -v202, v206, 1.0
	v_fmac_f32_e32 v206, v212, v206
	v_mul_f32_e32 v211, v210, v206
	v_fma_f32 v212, -v202, v211, v210
	v_fmac_f32_e32 v211, v212, v206
	v_fma_f32 v212, -v202, v211, v210
	v_div_fmas_f32 v212, v212, v206, v211
	v_div_fixup_f32 v70, v212, v198, v70
	v_div_scale_f32 v210, vcc, v71, v199, v71
	v_fma_f32 v212, -v203, v207, 1.0
	v_fmac_f32_e32 v207, v212, v207
	v_mul_f32_e32 v211, v210, v207
	v_fma_f32 v212, -v203, v211, v210
	v_fmac_f32_e32 v211, v212, v207
	v_fma_f32 v212, -v203, v211, v210
	v_div_fmas_f32 v212, v212, v207, v211
	v_div_fixup_f32 v71, v212, v199, v71
	v_div_scale_f32 v210, vcc, v72, v200, v72
	v_fma_f32 v212, -v204, v208, 1.0
	v_fmac_f32_e32 v208, v212, v208
	v_mul_f32_e32 v211, v210, v208
	v_fma_f32 v212, -v204, v211, v210
	v_fmac_f32_e32 v211, v212, v208
	v_fma_f32 v212, -v204, v211, v210
	v_div_fmas_f32 v212, v212, v208, v211
	v_div_fixup_f32 v72, v212, v200, v72
	v_div_scale_f32 v210, vcc, v73, v201, v73
	v_fma_f32 v212, -v205, v209, 1.0
	v_fmac_f32_e32 v209, v212, v209
	v_mul_f32_e32 v211, v210, v209
	v_fma_f32 v212, -v205, v211, v210
	v_fmac_f32_e32 v211, v212, v209
	v_fma_f32 v212, -v205, v211, v210
	v_div_fmas_f32 v212, v212, v209, v211
	v_div_fixup_f32 v73, v212, v201, v73
	v_mul_f32_e32 v198, 0xbfb8aa3b, v74
	v_mul_f32_e32 v199, 0xbfb8aa3b, v75
	v_mul_f32_e32 v200, 0xbfb8aa3b, v76
	v_mul_f32_e32 v201, 0xbfb8aa3b, v77
	v_exp_f32_e32 v198, v198
	v_exp_f32_e32 v199, v199
	v_exp_f32_e32 v200, v200
	v_exp_f32_e32 v201, v201
	s_nop 0
	v_add_f32_e32 v198, 1.0, v198
	v_add_f32_e32 v199, 1.0, v199
	v_add_f32_e32 v200, 1.0, v200
	v_add_f32_e32 v201, 1.0, v201
	v_div_scale_f32 v202, s[84:85], v198, v198, v74
	v_div_scale_f32 v203, s[84:85], v199, v199, v75
	v_div_scale_f32 v204, s[84:85], v200, v200, v76
	v_div_scale_f32 v205, s[84:85], v201, v201, v77
	v_rcp_f32_e32 v206, v202
	v_rcp_f32_e32 v207, v203
	v_rcp_f32_e32 v208, v204
	v_rcp_f32_e32 v209, v205
	s_nop 0
	v_div_scale_f32 v210, vcc, v74, v198, v74
	v_fma_f32 v212, -v202, v206, 1.0
	v_fmac_f32_e32 v206, v212, v206
	v_mul_f32_e32 v211, v210, v206
	v_fma_f32 v212, -v202, v211, v210
	v_fmac_f32_e32 v211, v212, v206
	v_fma_f32 v212, -v202, v211, v210
	v_div_fmas_f32 v212, v212, v206, v211
	v_div_fixup_f32 v74, v212, v198, v74
	v_div_scale_f32 v210, vcc, v75, v199, v75
	v_fma_f32 v212, -v203, v207, 1.0
	v_fmac_f32_e32 v207, v212, v207
	v_mul_f32_e32 v211, v210, v207
	v_fma_f32 v212, -v203, v211, v210
	v_fmac_f32_e32 v211, v212, v207
	v_fma_f32 v212, -v203, v211, v210
	v_div_fmas_f32 v212, v212, v207, v211
	v_div_fixup_f32 v75, v212, v199, v75
	v_div_scale_f32 v210, vcc, v76, v200, v76
	v_fma_f32 v212, -v204, v208, 1.0
	v_fmac_f32_e32 v208, v212, v208
	v_mul_f32_e32 v211, v210, v208
	v_fma_f32 v212, -v204, v211, v210
	v_fmac_f32_e32 v211, v212, v208
	v_fma_f32 v212, -v204, v211, v210
	v_div_fmas_f32 v212, v212, v208, v211
	v_div_fixup_f32 v76, v212, v200, v76
	v_div_scale_f32 v210, vcc, v77, v201, v77
	v_fma_f32 v212, -v205, v209, 1.0
	v_fmac_f32_e32 v209, v212, v209
	v_mul_f32_e32 v211, v210, v209
	v_fma_f32 v212, -v205, v211, v210
	v_fmac_f32_e32 v211, v212, v209
	v_fma_f32 v212, -v205, v211, v210
	v_div_fmas_f32 v212, v212, v209, v211
	v_div_fixup_f32 v77, v212, v201, v77
	v_mul_f32_e32 v198, 0xbfb8aa3b, v78
	v_mul_f32_e32 v199, 0xbfb8aa3b, v79
	v_mul_f32_e32 v200, 0xbfb8aa3b, v80
	v_mul_f32_e32 v201, 0xbfb8aa3b, v81
	v_exp_f32_e32 v198, v198
	v_exp_f32_e32 v199, v199
	v_exp_f32_e32 v200, v200
	v_exp_f32_e32 v201, v201
	s_nop 0
	v_add_f32_e32 v198, 1.0, v198
	v_add_f32_e32 v199, 1.0, v199
	v_add_f32_e32 v200, 1.0, v200
	v_add_f32_e32 v201, 1.0, v201
	v_div_scale_f32 v202, s[84:85], v198, v198, v78
	v_div_scale_f32 v203, s[84:85], v199, v199, v79
	v_div_scale_f32 v204, s[84:85], v200, v200, v80
	v_div_scale_f32 v205, s[84:85], v201, v201, v81
	v_rcp_f32_e32 v206, v202
	v_rcp_f32_e32 v207, v203
	v_rcp_f32_e32 v208, v204
	v_rcp_f32_e32 v209, v205
	s_nop 0
	v_div_scale_f32 v210, vcc, v78, v198, v78
	v_fma_f32 v212, -v202, v206, 1.0
	v_fmac_f32_e32 v206, v212, v206
	v_mul_f32_e32 v211, v210, v206
	v_fma_f32 v212, -v202, v211, v210
	v_fmac_f32_e32 v211, v212, v206
	v_fma_f32 v212, -v202, v211, v210
	v_div_fmas_f32 v212, v212, v206, v211
	v_div_fixup_f32 v78, v212, v198, v78
	v_div_scale_f32 v210, vcc, v79, v199, v79
	v_fma_f32 v212, -v203, v207, 1.0
	v_fmac_f32_e32 v207, v212, v207
	v_mul_f32_e32 v211, v210, v207
	v_fma_f32 v212, -v203, v211, v210
	v_fmac_f32_e32 v211, v212, v207
	v_fma_f32 v212, -v203, v211, v210
	v_div_fmas_f32 v212, v212, v207, v211
	v_div_fixup_f32 v79, v212, v199, v79
	v_div_scale_f32 v210, vcc, v80, v200, v80
	v_fma_f32 v212, -v204, v208, 1.0
	v_fmac_f32_e32 v208, v212, v208
	v_mul_f32_e32 v211, v210, v208
	v_fma_f32 v212, -v204, v211, v210
	v_fmac_f32_e32 v211, v212, v208
	v_fma_f32 v212, -v204, v211, v210
	v_div_fmas_f32 v212, v212, v208, v211
	v_div_fixup_f32 v80, v212, v200, v80
	v_div_scale_f32 v210, vcc, v81, v201, v81
	v_fma_f32 v212, -v205, v209, 1.0
	v_fmac_f32_e32 v209, v212, v209
	v_mul_f32_e32 v211, v210, v209
	v_fma_f32 v212, -v205, v211, v210
	v_fmac_f32_e32 v211, v212, v209
	v_fma_f32 v212, -v205, v211, v210
	v_div_fmas_f32 v212, v212, v209, v211
	v_div_fixup_f32 v81, v212, v201, v81
	v_mul_f32_e32 v198, 0xbfb8aa3b, v82
	v_mul_f32_e32 v199, 0xbfb8aa3b, v83
	v_mul_f32_e32 v200, 0xbfb8aa3b, v84
	v_mul_f32_e32 v201, 0xbfb8aa3b, v85
	v_exp_f32_e32 v198, v198
	v_exp_f32_e32 v199, v199
	v_exp_f32_e32 v200, v200
	v_exp_f32_e32 v201, v201
	s_nop 0
	v_add_f32_e32 v198, 1.0, v198
	v_add_f32_e32 v199, 1.0, v199
	v_add_f32_e32 v200, 1.0, v200
	v_add_f32_e32 v201, 1.0, v201
	v_div_scale_f32 v202, s[84:85], v198, v198, v82
	v_div_scale_f32 v203, s[84:85], v199, v199, v83
	v_div_scale_f32 v204, s[84:85], v200, v200, v84
	v_div_scale_f32 v205, s[84:85], v201, v201, v85
	v_rcp_f32_e32 v206, v202
	v_rcp_f32_e32 v207, v203
	v_rcp_f32_e32 v208, v204
	v_rcp_f32_e32 v209, v205
	s_nop 0
	v_div_scale_f32 v210, vcc, v82, v198, v82
	v_fma_f32 v212, -v202, v206, 1.0
	v_fmac_f32_e32 v206, v212, v206
	v_mul_f32_e32 v211, v210, v206
	v_fma_f32 v212, -v202, v211, v210
	v_fmac_f32_e32 v211, v212, v206
	v_fma_f32 v212, -v202, v211, v210
	v_div_fmas_f32 v212, v212, v206, v211
	v_div_fixup_f32 v82, v212, v198, v82
	v_div_scale_f32 v210, vcc, v83, v199, v83
	v_fma_f32 v212, -v203, v207, 1.0
	v_fmac_f32_e32 v207, v212, v207
	v_mul_f32_e32 v211, v210, v207
	v_fma_f32 v212, -v203, v211, v210
	v_fmac_f32_e32 v211, v212, v207
	v_fma_f32 v212, -v203, v211, v210
	v_div_fmas_f32 v212, v212, v207, v211
	v_div_fixup_f32 v83, v212, v199, v83
	v_div_scale_f32 v210, vcc, v84, v200, v84
	v_fma_f32 v212, -v204, v208, 1.0
	v_fmac_f32_e32 v208, v212, v208
	v_mul_f32_e32 v211, v210, v208
	v_fma_f32 v212, -v204, v211, v210
	v_fmac_f32_e32 v211, v212, v208
	v_fma_f32 v212, -v204, v211, v210
	v_div_fmas_f32 v212, v212, v208, v211
	v_div_fixup_f32 v84, v212, v200, v84
	v_div_scale_f32 v210, vcc, v85, v201, v85
	v_fma_f32 v212, -v205, v209, 1.0
	v_fmac_f32_e32 v209, v212, v209
	v_mul_f32_e32 v211, v210, v209
	v_fma_f32 v212, -v205, v211, v210
	v_fmac_f32_e32 v211, v212, v209
	v_fma_f32 v212, -v205, v211, v210
	v_div_fmas_f32 v212, v212, v209, v211
	v_div_fixup_f32 v85, v212, v201, v85
	v_mul_f32_e32 v198, 0xbfb8aa3b, v86
	v_mul_f32_e32 v199, 0xbfb8aa3b, v87
	v_mul_f32_e32 v200, 0xbfb8aa3b, v88
	v_mul_f32_e32 v201, 0xbfb8aa3b, v89
	v_exp_f32_e32 v198, v198
	v_exp_f32_e32 v199, v199
	v_exp_f32_e32 v200, v200
	v_exp_f32_e32 v201, v201
	s_nop 0
	v_add_f32_e32 v198, 1.0, v198
	v_add_f32_e32 v199, 1.0, v199
	v_add_f32_e32 v200, 1.0, v200
	v_add_f32_e32 v201, 1.0, v201
	v_div_scale_f32 v202, s[84:85], v198, v198, v86
	v_div_scale_f32 v203, s[84:85], v199, v199, v87
	v_div_scale_f32 v204, s[84:85], v200, v200, v88
	v_div_scale_f32 v205, s[84:85], v201, v201, v89
	v_rcp_f32_e32 v206, v202
	v_rcp_f32_e32 v207, v203
	v_rcp_f32_e32 v208, v204
	v_rcp_f32_e32 v209, v205
	s_nop 0
	v_div_scale_f32 v210, vcc, v86, v198, v86
	v_fma_f32 v212, -v202, v206, 1.0
	v_fmac_f32_e32 v206, v212, v206
	v_mul_f32_e32 v211, v210, v206
	v_fma_f32 v212, -v202, v211, v210
	v_fmac_f32_e32 v211, v212, v206
	v_fma_f32 v212, -v202, v211, v210
	v_div_fmas_f32 v212, v212, v206, v211
	v_div_fixup_f32 v86, v212, v198, v86
	v_div_scale_f32 v210, vcc, v87, v199, v87
	v_fma_f32 v212, -v203, v207, 1.0
	v_fmac_f32_e32 v207, v212, v207
	v_mul_f32_e32 v211, v210, v207
	v_fma_f32 v212, -v203, v211, v210
	v_fmac_f32_e32 v211, v212, v207
	v_fma_f32 v212, -v203, v211, v210
	v_div_fmas_f32 v212, v212, v207, v211
	v_div_fixup_f32 v87, v212, v199, v87
	v_div_scale_f32 v210, vcc, v88, v200, v88
	v_fma_f32 v212, -v204, v208, 1.0
	v_fmac_f32_e32 v208, v212, v208
	v_mul_f32_e32 v211, v210, v208
	v_fma_f32 v212, -v204, v211, v210
	v_fmac_f32_e32 v211, v212, v208
	v_fma_f32 v212, -v204, v211, v210
	v_div_fmas_f32 v212, v212, v208, v211
	v_div_fixup_f32 v88, v212, v200, v88
	v_div_scale_f32 v210, vcc, v89, v201, v89
	v_fma_f32 v212, -v205, v209, 1.0
	v_fmac_f32_e32 v209, v212, v209
	v_mul_f32_e32 v211, v210, v209
	v_fma_f32 v212, -v205, v211, v210
	v_fmac_f32_e32 v211, v212, v209
	v_fma_f32 v212, -v205, v211, v210
	v_div_fmas_f32 v212, v212, v209, v211
	v_div_fixup_f32 v89, v212, v201, v89
	v_mul_f32_e32 v198, 0xbfb8aa3b, v90
	v_mul_f32_e32 v199, 0xbfb8aa3b, v91
	v_mul_f32_e32 v200, 0xbfb8aa3b, v92
	v_mul_f32_e32 v201, 0xbfb8aa3b, v93
	v_exp_f32_e32 v198, v198
	v_exp_f32_e32 v199, v199
	v_exp_f32_e32 v200, v200
	v_exp_f32_e32 v201, v201
	s_nop 0
	v_add_f32_e32 v198, 1.0, v198
	v_add_f32_e32 v199, 1.0, v199
	v_add_f32_e32 v200, 1.0, v200
	v_add_f32_e32 v201, 1.0, v201
	v_div_scale_f32 v202, s[84:85], v198, v198, v90
	v_div_scale_f32 v203, s[84:85], v199, v199, v91
	v_div_scale_f32 v204, s[84:85], v200, v200, v92
	v_div_scale_f32 v205, s[84:85], v201, v201, v93
	v_rcp_f32_e32 v206, v202
	v_rcp_f32_e32 v207, v203
	v_rcp_f32_e32 v208, v204
	v_rcp_f32_e32 v209, v205
	s_nop 0
	v_div_scale_f32 v210, vcc, v90, v198, v90
	v_fma_f32 v212, -v202, v206, 1.0
	v_fmac_f32_e32 v206, v212, v206
	v_mul_f32_e32 v211, v210, v206
	v_fma_f32 v212, -v202, v211, v210
	v_fmac_f32_e32 v211, v212, v206
	v_fma_f32 v212, -v202, v211, v210
	v_div_fmas_f32 v212, v212, v206, v211
	v_div_fixup_f32 v90, v212, v198, v90
	v_div_scale_f32 v210, vcc, v91, v199, v91
	v_fma_f32 v212, -v203, v207, 1.0
	v_fmac_f32_e32 v207, v212, v207
	v_mul_f32_e32 v211, v210, v207
	v_fma_f32 v212, -v203, v211, v210
	v_fmac_f32_e32 v211, v212, v207
	v_fma_f32 v212, -v203, v211, v210
	v_div_fmas_f32 v212, v212, v207, v211
	v_div_fixup_f32 v91, v212, v199, v91
	v_div_scale_f32 v210, vcc, v92, v200, v92
	v_fma_f32 v212, -v204, v208, 1.0
	v_fmac_f32_e32 v208, v212, v208
	v_mul_f32_e32 v211, v210, v208
	v_fma_f32 v212, -v204, v211, v210
	v_fmac_f32_e32 v211, v212, v208
	v_fma_f32 v212, -v204, v211, v210
	v_div_fmas_f32 v212, v212, v208, v211
	v_div_fixup_f32 v92, v212, v200, v92
	v_div_scale_f32 v210, vcc, v93, v201, v93
	v_fma_f32 v212, -v205, v209, 1.0
	v_fmac_f32_e32 v209, v212, v209
	v_mul_f32_e32 v211, v210, v209
	v_fma_f32 v212, -v205, v211, v210
	v_fmac_f32_e32 v211, v212, v209
	v_fma_f32 v212, -v205, v211, v210
	v_div_fmas_f32 v212, v212, v209, v211
	v_div_fixup_f32 v93, v212, v201, v93
	v_mul_f32_e32 v198, 0xbfb8aa3b, v94
	v_mul_f32_e32 v199, 0xbfb8aa3b, v95
	v_mul_f32_e32 v200, 0xbfb8aa3b, v96
	v_mul_f32_e32 v201, 0xbfb8aa3b, v97
	v_exp_f32_e32 v198, v198
	v_exp_f32_e32 v199, v199
	v_exp_f32_e32 v200, v200
	v_exp_f32_e32 v201, v201
	s_nop 0
	v_add_f32_e32 v198, 1.0, v198
	v_add_f32_e32 v199, 1.0, v199
	v_add_f32_e32 v200, 1.0, v200
	v_add_f32_e32 v201, 1.0, v201
	v_div_scale_f32 v202, s[84:85], v198, v198, v94
	v_div_scale_f32 v203, s[84:85], v199, v199, v95
	v_div_scale_f32 v204, s[84:85], v200, v200, v96
	v_div_scale_f32 v205, s[84:85], v201, v201, v97
	v_rcp_f32_e32 v206, v202
	v_rcp_f32_e32 v207, v203
	v_rcp_f32_e32 v208, v204
	v_rcp_f32_e32 v209, v205
	s_nop 0
	v_div_scale_f32 v210, vcc, v94, v198, v94
	v_fma_f32 v212, -v202, v206, 1.0
	v_fmac_f32_e32 v206, v212, v206
	v_mul_f32_e32 v211, v210, v206
	v_fma_f32 v212, -v202, v211, v210
	v_fmac_f32_e32 v211, v212, v206
	v_fma_f32 v212, -v202, v211, v210
	v_div_fmas_f32 v212, v212, v206, v211
	v_div_fixup_f32 v94, v212, v198, v94
	v_div_scale_f32 v210, vcc, v95, v199, v95
	v_fma_f32 v212, -v203, v207, 1.0
	v_fmac_f32_e32 v207, v212, v207
	v_mul_f32_e32 v211, v210, v207
	v_fma_f32 v212, -v203, v211, v210
	v_fmac_f32_e32 v211, v212, v207
	v_fma_f32 v212, -v203, v211, v210
	v_div_fmas_f32 v212, v212, v207, v211
	v_div_fixup_f32 v95, v212, v199, v95
	v_div_scale_f32 v210, vcc, v96, v200, v96
	v_fma_f32 v212, -v204, v208, 1.0
	v_fmac_f32_e32 v208, v212, v208
	v_mul_f32_e32 v211, v210, v208
	v_fma_f32 v212, -v204, v211, v210
	v_fmac_f32_e32 v211, v212, v208
	v_fma_f32 v212, -v204, v211, v210
	v_div_fmas_f32 v212, v212, v208, v211
	v_div_fixup_f32 v96, v212, v200, v96
	v_div_scale_f32 v210, vcc, v97, v201, v97
	v_fma_f32 v212, -v205, v209, 1.0
	v_fmac_f32_e32 v209, v212, v209
	v_mul_f32_e32 v211, v210, v209
	v_fma_f32 v212, -v205, v211, v210
	v_fmac_f32_e32 v211, v212, v209
	v_fma_f32 v212, -v205, v211, v210
	v_div_fmas_f32 v212, v212, v209, v211
	v_div_fixup_f32 v97, v212, v201, v97
	v_and_b32_e32 v223, 31, v0
	v_mul_u32_u24_e32 v220, 0x110, v223
	v_bfe_u32 v223, v0, 5, 1
	v_lshl_add_u32 v220, v223, 4, v220
	v_bfe_u32 v224, v0, 6, 2
	v_mul_u32_u24_e32 v223, 0x2200, v224
	v_add_u32_e32 v220, v220, v223
	v_bfe_u32 v222, v0, 4, 2
	v_mul_u32_u24_e32 v221, 0x110, v222
	v_add_u32_e32 v221, v221, v223
	v_and_b32_e32 v223, 15, v0
	v_lshl_add_u32 v221, v223, 4, v221
	s_lshr_b32 s85, s64, 6
	s_sub_u32 s85, s85, 24
	s_lshl_b32 s85, s85, 8
	s_and_b32 s84, s64, 63
	s_mulk_i32 s84, 0xc0
	v_lshrrev_b32_e32 v224, 1, v224
	v_mul_u32_u24_e32 v224, 0x60, v224
	v_add3_u32 v222, v222, v224, s84
	v_lshlrev_b32_e32 v222, 11, v222
	v_lshl_add_u32 v222, v223, 3, v222
	v_bfe_u32 v223, v0, 6, 1
	v_lshl_add_u32 v222, v223, 7, v222
	v_add_u32_e32 v222, s85, v222
	ds_write_b128 v220, v[82:85]
	ds_write_b128 v220, v[86:89] offset:32
	ds_write_b128 v220, v[90:93] offset:64
	ds_write_b128 v220, v[94:97] offset:96
	ds_write_b128 v220, v[66:69] offset:128
	ds_write_b128 v220, v[70:73] offset:160
	ds_write_b128 v220, v[74:77] offset:192
	ds_write_b128 v220, v[78:81] offset:224
	v_mov_b32_e32 v230, v222
	v_add_u32_e32 v231, 0x2000, v222
	v_add_u32_e32 v232, 0x4000, v222
	v_add_u32_e32 v233, 0x6000, v222
	v_add_u32_e32 v234, 0x8000, v222
	v_add_u32_e32 v235, 0xa000, v222
	v_add_u32_e32 v236, 0xc000, v222
	v_add_u32_e32 v237, 0xe000, v222
	s_waitcnt lgkmcnt(0)
	ds_read_b128 v[82:85], v221
	ds_read_b128 v[86:89], v221 offset:1088
	ds_read_b128 v[90:93], v221 offset:2176
	ds_read_b128 v[94:97], v221 offset:3264
	ds_read_b128 v[66:69], v221 offset:4352
	ds_read_b128 v[70:73], v221 offset:5440
	ds_read_b128 v[74:77], v221 offset:6528
	ds_read_b128 v[78:81], v221 offset:7616
	s_waitcnt lgkmcnt(7)
	v_cvt_pk_bf16_f32 v82, v82, v83
	v_cvt_pk_bf16_f32 v83, v84, v85
	global_store_dwordx2 v230, v[82:83], s[82:83]
	s_waitcnt lgkmcnt(6)
	v_cvt_pk_bf16_f32 v86, v86, v87
	v_cvt_pk_bf16_f32 v87, v88, v89
	global_store_dwordx2 v231, v[86:87], s[82:83]
	s_waitcnt lgkmcnt(5)
	v_cvt_pk_bf16_f32 v90, v90, v91
	v_cvt_pk_bf16_f32 v91, v92, v93
	global_store_dwordx2 v232, v[90:91], s[82:83]
	s_waitcnt lgkmcnt(4)
	v_cvt_pk_bf16_f32 v94, v94, v95
	v_cvt_pk_bf16_f32 v95, v96, v97
	global_store_dwordx2 v233, v[94:95], s[82:83]
	s_waitcnt lgkmcnt(3)
	v_cvt_pk_bf16_f32 v66, v66, v67
	v_cvt_pk_bf16_f32 v67, v68, v69
	global_store_dwordx2 v234, v[66:67], s[82:83]
	s_waitcnt lgkmcnt(2)
	v_cvt_pk_bf16_f32 v70, v70, v71
	v_cvt_pk_bf16_f32 v71, v72, v73
	global_store_dwordx2 v235, v[70:71], s[82:83]
	s_waitcnt lgkmcnt(1)
	v_cvt_pk_bf16_f32 v74, v74, v75
	v_cvt_pk_bf16_f32 v75, v76, v77
	global_store_dwordx2 v236, v[74:75], s[82:83]
	s_waitcnt lgkmcnt(0)
	v_cvt_pk_bf16_f32 v78, v78, v79
	v_cvt_pk_bf16_f32 v79, v80, v81
	global_store_dwordx2 v237, v[78:79], s[82:83]
	ds_write_b128 v220, v[50:53]
	ds_write_b128 v220, v[54:57] offset:32
	ds_write_b128 v220, v[58:61] offset:64
	ds_write_b128 v220, v[62:65] offset:96
	ds_write_b128 v220, v[34:37] offset:128
	ds_write_b128 v220, v[38:41] offset:160
	ds_write_b128 v220, v[42:45] offset:192
	ds_write_b128 v220, v[46:49] offset:224
	v_add_u32_e32 v230, 0x10000, v222
	v_add_u32_e32 v231, 0x12000, v222
	v_add_u32_e32 v232, 0x14000, v222
	v_add_u32_e32 v233, 0x16000, v222
	v_add_u32_e32 v234, 0x18000, v222
	v_add_u32_e32 v235, 0x1a000, v222
	v_add_u32_e32 v236, 0x1c000, v222
	v_add_u32_e32 v237, 0x1e000, v222
	s_waitcnt lgkmcnt(0)
	ds_read_b128 v[50:53], v221
	ds_read_b128 v[54:57], v221 offset:1088
	ds_read_b128 v[58:61], v221 offset:2176
	ds_read_b128 v[62:65], v221 offset:3264
	ds_read_b128 v[34:37], v221 offset:4352
	ds_read_b128 v[38:41], v221 offset:5440
	ds_read_b128 v[42:45], v221 offset:6528
	ds_read_b128 v[46:49], v221 offset:7616
	s_waitcnt lgkmcnt(7)
	v_cvt_pk_bf16_f32 v50, v50, v51
	v_cvt_pk_bf16_f32 v51, v52, v53
	global_store_dwordx2 v230, v[50:51], s[82:83]
	s_waitcnt lgkmcnt(6)
	v_cvt_pk_bf16_f32 v54, v54, v55
	v_cvt_pk_bf16_f32 v55, v56, v57
	global_store_dwordx2 v231, v[54:55], s[82:83]
	s_waitcnt lgkmcnt(5)
	v_cvt_pk_bf16_f32 v58, v58, v59
	v_cvt_pk_bf16_f32 v59, v60, v61
	global_store_dwordx2 v232, v[58:59], s[82:83]
	s_waitcnt lgkmcnt(4)
	v_cvt_pk_bf16_f32 v62, v62, v63
	v_cvt_pk_bf16_f32 v63, v64, v65
	global_store_dwordx2 v233, v[62:63], s[82:83]
	s_waitcnt lgkmcnt(3)
	v_cvt_pk_bf16_f32 v34, v34, v35
	v_cvt_pk_bf16_f32 v35, v36, v37
	global_store_dwordx2 v234, v[34:35], s[82:83]
	s_waitcnt lgkmcnt(2)
	v_cvt_pk_bf16_f32 v38, v38, v39
	v_cvt_pk_bf16_f32 v39, v40, v41
	global_store_dwordx2 v235, v[38:39], s[82:83]
	s_waitcnt lgkmcnt(1)
	v_cvt_pk_bf16_f32 v42, v42, v43
	v_cvt_pk_bf16_f32 v43, v44, v45
	global_store_dwordx2 v236, v[42:43], s[82:83]
	s_waitcnt lgkmcnt(0)
	v_cvt_pk_bf16_f32 v46, v46, v47
	v_cvt_pk_bf16_f32 v47, v48, v49
	global_store_dwordx2 v237, v[46:47], s[82:83]
	ds_write_b128 v220, v[18:21]
	ds_write_b128 v220, v[22:25] offset:32
	ds_write_b128 v220, v[26:29] offset:64
	ds_write_b128 v220, v[30:33] offset:96
	ds_write_b128 v220, v[2:5] offset:128
	ds_write_b128 v220, v[6:9] offset:160
	ds_write_b128 v220, v[10:13] offset:192
	ds_write_b128 v220, v[14:17] offset:224
	v_add_u32_e32 v230, 0x20000, v222
	v_add_u32_e32 v231, 0x22000, v222
	v_add_u32_e32 v232, 0x24000, v222
	v_add_u32_e32 v233, 0x26000, v222
	v_add_u32_e32 v234, 0x28000, v222
	v_add_u32_e32 v235, 0x2a000, v222
	v_add_u32_e32 v236, 0x2c000, v222
	v_add_u32_e32 v237, 0x2e000, v222
	s_waitcnt lgkmcnt(0)
	ds_read_b128 v[18:21], v221
	ds_read_b128 v[22:25], v221 offset:1088
	ds_read_b128 v[26:29], v221 offset:2176
	ds_read_b128 v[30:33], v221 offset:3264
	ds_read_b128 v[2:5], v221 offset:4352
	ds_read_b128 v[6:9], v221 offset:5440
	ds_read_b128 v[10:13], v221 offset:6528
	ds_read_b128 v[14:17], v221 offset:7616
	s_waitcnt lgkmcnt(7)
	v_cvt_pk_bf16_f32 v18, v18, v19
	v_cvt_pk_bf16_f32 v19, v20, v21
	global_store_dwordx2 v230, v[18:19], s[82:83]
	s_waitcnt lgkmcnt(6)
	v_cvt_pk_bf16_f32 v22, v22, v23
	v_cvt_pk_bf16_f32 v23, v24, v25
	global_store_dwordx2 v231, v[22:23], s[82:83]
	s_waitcnt lgkmcnt(5)
	v_cvt_pk_bf16_f32 v26, v26, v27
	v_cvt_pk_bf16_f32 v27, v28, v29
	global_store_dwordx2 v232, v[26:27], s[82:83]
	s_waitcnt lgkmcnt(4)
	v_cvt_pk_bf16_f32 v30, v30, v31
	v_cvt_pk_bf16_f32 v31, v32, v33
	global_store_dwordx2 v233, v[30:31], s[82:83]
	s_waitcnt lgkmcnt(3)
	v_cvt_pk_bf16_f32 v2, v2, v3
	v_cvt_pk_bf16_f32 v3, v4, v5
	global_store_dwordx2 v234, v[2:3], s[82:83]
	s_waitcnt lgkmcnt(2)
	v_cvt_pk_bf16_f32 v6, v6, v7
	v_cvt_pk_bf16_f32 v7, v8, v9
	global_store_dwordx2 v235, v[6:7], s[82:83]
	s_waitcnt lgkmcnt(1)
	v_cvt_pk_bf16_f32 v10, v10, v11
	v_cvt_pk_bf16_f32 v11, v12, v13
	global_store_dwordx2 v236, v[10:11], s[82:83]
	s_waitcnt lgkmcnt(0)
	v_cvt_pk_bf16_f32 v14, v14, v15
	v_cvt_pk_bf16_f32 v15, v16, v17
	global_store_dwordx2 v237, v[14:15], s[82:83]
	s_barrier
	s_branch .LBB0_1266

G1E_ph13_NK:
	s_load_dwordx2 s[82:83], s[0:1], 0x168
	s_and_b32 s84, s64, 63
	s_cmp_gt_u32 s84, 21
	s_cbranch_scc1 G1E_ph13_NK2
	v_and_b32_e32 v223, 31, v0
	v_mul_u32_u24_e32 v220, 0x110, v223
	v_bfe_u32 v223, v0, 5, 1
	v_lshl_add_u32 v220, v223, 4, v220
	v_bfe_u32 v224, v0, 6, 2
	v_mul_u32_u24_e32 v223, 0x2200, v224
	v_add_u32_e32 v220, v220, v223
	v_bfe_u32 v222, v0, 4, 2
	v_mul_u32_u24_e32 v221, 0x110, v222
	v_add_u32_e32 v221, v221, v223
	v_and_b32_e32 v223, 15, v0
	v_lshl_add_u32 v221, v223, 4, v221
	s_lshr_b32 s85, s64, 6
	s_sub_u32 s85, s85, 8
	s_lshl_b32 s85, s85, 8
	s_and_b32 s84, s64, 63
	s_mulk_i32 s84, 0xc0
	v_lshrrev_b32_e32 v224, 1, v224
	v_mul_u32_u24_e32 v224, 0x60, v224
	v_add3_u32 v222, v222, v224, s84
	v_lshlrev_b32_e32 v225, 3, v223
	v_bfe_u32 v223, v0, 6, 1
	v_lshl_add_u32 v225, v223, 7, v225
	v_add_u32_e32 v225, s85, v225
	s_load_dwordx2 s[86:87], s[0:1], 0x80
	s_movk_i32 s90, 0x1000
	ds_write_b128 v220, v[82:85]
	ds_write_b128 v220, v[86:89] offset:32
	ds_write_b128 v220, v[90:93] offset:64
	ds_write_b128 v220, v[94:97] offset:96
	ds_write_b128 v220, v[66:69] offset:128
	ds_write_b128 v220, v[70:73] offset:160
	ds_write_b128 v220, v[74:77] offset:192
	ds_write_b128 v220, v[78:81] offset:224
	v_add_u32_e32 v226, 0, v222
	v_lshlrev_b32_e32 v238, 12, v226
	v_lshl_add_u32 v238, v225, 1, v238
	v_cmp_gt_i32_e64 s[66:67], s90, v226
	v_add_u32_e32 v227, 0xfffff000, v226
	v_ashrrev_i32_e32 v227, 11, v227
	v_add_u32_e32 v227, 1, v227
	v_max_i32_e32 v227, 0, v227
	v_lshl_add_u32 v226, v227, 8, v226
	v_lshl_add_u32 v230, v226, 11, v225
	v_add_u32_e32 v226, 4, v222
	v_lshlrev_b32_e32 v239, 12, v226
	v_lshl_add_u32 v239, v225, 1, v239
	v_cmp_gt_i32_e64 s[68:69], s90, v226
	v_add_u32_e32 v227, 0xfffff000, v226
	v_ashrrev_i32_e32 v227, 11, v227
	v_add_u32_e32 v227, 1, v227
	v_max_i32_e32 v227, 0, v227
	v_lshl_add_u32 v226, v227, 8, v226
	v_lshl_add_u32 v231, v226, 11, v225
	v_add_u32_e32 v226, 8, v222
	v_lshlrev_b32_e32 v240, 12, v226
	v_lshl_add_u32 v240, v225, 1, v240
	v_cmp_gt_i32_e64 s[70:71], s90, v226
	v_add_u32_e32 v227, 0xfffff000, v226
	v_ashrrev_i32_e32 v227, 11, v227
	v_add_u32_e32 v227, 1, v227
	v_max_i32_e32 v227, 0, v227
	v_lshl_add_u32 v226, v227, 8, v226
	v_lshl_add_u32 v232, v226, 11, v225
	v_add_u32_e32 v226, 12, v222
	v_lshlrev_b32_e32 v241, 12, v226
	v_lshl_add_u32 v241, v225, 1, v241
	v_cmp_gt_i32_e64 s[72:73], s90, v226
	v_add_u32_e32 v227, 0xfffff000, v226
	v_ashrrev_i32_e32 v227, 11, v227
	v_add_u32_e32 v227, 1, v227
	v_max_i32_e32 v227, 0, v227
	v_lshl_add_u32 v226, v227, 8, v226
	v_lshl_add_u32 v233, v226, 11, v225
	v_add_u32_e32 v226, 16, v222
	v_lshlrev_b32_e32 v242, 12, v226
	v_lshl_add_u32 v242, v225, 1, v242
	v_cmp_gt_i32_e64 s[74:75], s90, v226
	v_add_u32_e32 v227, 0xfffff000, v226
	v_ashrrev_i32_e32 v227, 11, v227
	v_add_u32_e32 v227, 1, v227
	v_max_i32_e32 v227, 0, v227
	v_lshl_add_u32 v226, v227, 8, v226
	v_lshl_add_u32 v234, v226, 11, v225
	v_add_u32_e32 v226, 20, v222
	v_lshlrev_b32_e32 v243, 12, v226
	v_lshl_add_u32 v243, v225, 1, v243
	v_cmp_gt_i32_e64 s[76:77], s90, v226
	v_add_u32_e32 v227, 0xfffff000, v226
	v_ashrrev_i32_e32 v227, 11, v227
	v_add_u32_e32 v227, 1, v227
	v_max_i32_e32 v227, 0, v227
	v_lshl_add_u32 v226, v227, 8, v226
	v_lshl_add_u32 v235, v226, 11, v225
	v_add_u32_e32 v226, 24, v222
	v_lshlrev_b32_e32 v244, 12, v226
	v_lshl_add_u32 v244, v225, 1, v244
	v_cmp_gt_i32_e64 s[78:79], s90, v226
	v_add_u32_e32 v227, 0xfffff000, v226
	v_ashrrev_i32_e32 v227, 11, v227
	v_add_u32_e32 v227, 1, v227
	v_max_i32_e32 v227, 0, v227
	v_lshl_add_u32 v226, v227, 8, v226
	v_lshl_add_u32 v236, v226, 11, v225
	v_add_u32_e32 v226, 28, v222
	v_lshlrev_b32_e32 v245, 12, v226
	v_lshl_add_u32 v245, v225, 1, v245
	v_cmp_gt_i32_e64 s[80:81], s90, v226
	v_add_u32_e32 v227, 0xfffff000, v226
	v_ashrrev_i32_e32 v227, 11, v227
	v_add_u32_e32 v227, 1, v227
	v_max_i32_e32 v227, 0, v227
	v_lshl_add_u32 v226, v227, 8, v226
	v_lshl_add_u32 v237, v226, 11, v225
	s_waitcnt lgkmcnt(0)
	s_add_u32 s86, s86, 0x3500000
	s_addc_u32 s87, s87, 0
	ds_read_b128 v[82:85], v221
	ds_read_b128 v[86:89], v221 offset:1088
	ds_read_b128 v[90:93], v221 offset:2176
	ds_read_b128 v[94:97], v221 offset:3264
	ds_read_b128 v[66:69], v221 offset:4352
	ds_read_b128 v[70:73], v221 offset:5440
	ds_read_b128 v[74:77], v221 offset:6528
	ds_read_b128 v[78:81], v221 offset:7616
	s_waitcnt lgkmcnt(7)
	s_and_saveexec_b64 s[88:89], s[66:67]
	global_store_dwordx4 v238, v[82:85], s[86:87] nt
	s_mov_b64 exec, s[88:89]
	s_nop 1
	v_cvt_pk_bf16_f32 v82, v82, v83
	v_cvt_pk_bf16_f32 v83, v84, v85
	global_store_dwordx2 v230, v[82:83], s[82:83]
	s_waitcnt lgkmcnt(6)
	s_and_saveexec_b64 s[88:89], s[68:69]
	global_store_dwordx4 v239, v[86:89], s[86:87] nt
	s_mov_b64 exec, s[88:89]
	s_nop 1
	v_cvt_pk_bf16_f32 v86, v86, v87
	v_cvt_pk_bf16_f32 v87, v88, v89
	global_store_dwordx2 v231, v[86:87], s[82:83]
	s_waitcnt lgkmcnt(5)
	s_and_saveexec_b64 s[88:89], s[70:71]
	global_store_dwordx4 v240, v[90:93], s[86:87] nt
	s_mov_b64 exec, s[88:89]
	s_nop 1
	v_cvt_pk_bf16_f32 v90, v90, v91
	v_cvt_pk_bf16_f32 v91, v92, v93
	global_store_dwordx2 v232, v[90:91], s[82:83]
	s_waitcnt lgkmcnt(4)
	s_and_saveexec_b64 s[88:89], s[72:73]
	global_store_dwordx4 v241, v[94:97], s[86:87] nt
	s_mov_b64 exec, s[88:89]
	s_nop 1
	v_cvt_pk_bf16_f32 v94, v94, v95
	v_cvt_pk_bf16_f32 v95, v96, v97
	global_store_dwordx2 v233, v[94:95], s[82:83]
	s_waitcnt lgkmcnt(3)
	s_and_saveexec_b64 s[88:89], s[74:75]
	global_store_dwordx4 v242, v[66:69], s[86:87] nt
	s_mov_b64 exec, s[88:89]
	s_nop 1
	v_cvt_pk_bf16_f32 v66, v66, v67
	v_cvt_pk_bf16_f32 v67, v68, v69
	global_store_dwordx2 v234, v[66:67], s[82:83]
	s_waitcnt lgkmcnt(2)
	s_and_saveexec_b64 s[88:89], s[76:77]
	global_store_dwordx4 v243, v[70:73], s[86:87] nt
	s_mov_b64 exec, s[88:89]
	s_nop 1
	v_cvt_pk_bf16_f32 v70, v70, v71
	v_cvt_pk_bf16_f32 v71, v72, v73
	global_store_dwordx2 v235, v[70:71], s[82:83]
	s_waitcnt lgkmcnt(1)
	s_and_saveexec_b64 s[88:89], s[78:79]
	global_store_dwordx4 v244, v[74:77], s[86:87] nt
	s_mov_b64 exec, s[88:89]
	s_nop 1
	v_cvt_pk_bf16_f32 v74, v74, v75
	v_cvt_pk_bf16_f32 v75, v76, v77
	global_store_dwordx2 v236, v[74:75], s[82:83]
	s_waitcnt lgkmcnt(0)
	s_and_saveexec_b64 s[88:89], s[80:81]
	global_store_dwordx4 v245, v[78:81], s[86:87] nt
	s_mov_b64 exec, s[88:89]
	s_nop 1
	v_cvt_pk_bf16_f32 v78, v78, v79
	v_cvt_pk_bf16_f32 v79, v80, v81
	global_store_dwordx2 v237, v[78:79], s[82:83]
	ds_write_b128 v220, v[50:53]
	ds_write_b128 v220, v[54:57] offset:32
	ds_write_b128 v220, v[58:61] offset:64
	ds_write_b128 v220, v[62:65] offset:96
	ds_write_b128 v220, v[34:37] offset:128
	ds_write_b128 v220, v[38:41] offset:160
	ds_write_b128 v220, v[42:45] offset:192
	ds_write_b128 v220, v[46:49] offset:224
	v_add_u32_e32 v226, 32, v222
	v_lshlrev_b32_e32 v238, 12, v226
	v_lshl_add_u32 v238, v225, 1, v238
	v_cmp_gt_i32_e64 s[66:67], s90, v226
	v_add_u32_e32 v227, 0xfffff000, v226
	v_ashrrev_i32_e32 v227, 11, v227
	v_add_u32_e32 v227, 1, v227
	v_max_i32_e32 v227, 0, v227
	v_lshl_add_u32 v226, v227, 8, v226
	v_lshl_add_u32 v230, v226, 11, v225
	v_add_u32_e32 v226, 36, v222
	v_lshlrev_b32_e32 v239, 12, v226
	v_lshl_add_u32 v239, v225, 1, v239
	v_cmp_gt_i32_e64 s[68:69], s90, v226
	v_add_u32_e32 v227, 0xfffff000, v226
	v_ashrrev_i32_e32 v227, 11, v227
	v_add_u32_e32 v227, 1, v227
	v_max_i32_e32 v227, 0, v227
	v_lshl_add_u32 v226, v227, 8, v226
	v_lshl_add_u32 v231, v226, 11, v225
	v_add_u32_e32 v226, 40, v222
	v_lshlrev_b32_e32 v240, 12, v226
	v_lshl_add_u32 v240, v225, 1, v240
	v_cmp_gt_i32_e64 s[70:71], s90, v226
	v_add_u32_e32 v227, 0xfffff000, v226
	v_ashrrev_i32_e32 v227, 11, v227
	v_add_u32_e32 v227, 1, v227
	v_max_i32_e32 v227, 0, v227
	v_lshl_add_u32 v226, v227, 8, v226
	v_lshl_add_u32 v232, v226, 11, v225
	v_add_u32_e32 v226, 44, v222
	v_lshlrev_b32_e32 v241, 12, v226
	v_lshl_add_u32 v241, v225, 1, v241
	v_cmp_gt_i32_e64 s[72:73], s90, v226
	v_add_u32_e32 v227, 0xfffff000, v226
	v_ashrrev_i32_e32 v227, 11, v227
	v_add_u32_e32 v227, 1, v227
	v_max_i32_e32 v227, 0, v227
	v_lshl_add_u32 v226, v227, 8, v226
	v_lshl_add_u32 v233, v226, 11, v225
	v_add_u32_e32 v226, 48, v222
	v_lshlrev_b32_e32 v242, 12, v226
	v_lshl_add_u32 v242, v225, 1, v242
	v_cmp_gt_i32_e64 s[74:75], s90, v226
	v_add_u32_e32 v227, 0xfffff000, v226
	v_ashrrev_i32_e32 v227, 11, v227
	v_add_u32_e32 v227, 1, v227
	v_max_i32_e32 v227, 0, v227
	v_lshl_add_u32 v226, v227, 8, v226
	v_lshl_add_u32 v234, v226, 11, v225
	v_add_u32_e32 v226, 52, v222
	v_lshlrev_b32_e32 v243, 12, v226
	v_lshl_add_u32 v243, v225, 1, v243
	v_cmp_gt_i32_e64 s[76:77], s90, v226
	v_add_u32_e32 v227, 0xfffff000, v226
	v_ashrrev_i32_e32 v227, 11, v227
	v_add_u32_e32 v227, 1, v227
	v_max_i32_e32 v227, 0, v227
	v_lshl_add_u32 v226, v227, 8, v226
	v_lshl_add_u32 v235, v226, 11, v225
	v_add_u32_e32 v226, 56, v222
	v_lshlrev_b32_e32 v244, 12, v226
	v_lshl_add_u32 v244, v225, 1, v244
	v_cmp_gt_i32_e64 s[78:79], s90, v226
	v_add_u32_e32 v227, 0xfffff000, v226
	v_ashrrev_i32_e32 v227, 11, v227
	v_add_u32_e32 v227, 1, v227
	v_max_i32_e32 v227, 0, v227
	v_lshl_add_u32 v226, v227, 8, v226
	v_lshl_add_u32 v236, v226, 11, v225
	v_add_u32_e32 v226, 60, v222
	v_lshlrev_b32_e32 v245, 12, v226
	v_lshl_add_u32 v245, v225, 1, v245
	v_cmp_gt_i32_e64 s[80:81], s90, v226
	v_add_u32_e32 v227, 0xfffff000, v226
	v_ashrrev_i32_e32 v227, 11, v227
	v_add_u32_e32 v227, 1, v227
	v_max_i32_e32 v227, 0, v227
	v_lshl_add_u32 v226, v227, 8, v226
	v_lshl_add_u32 v237, v226, 11, v225
	s_waitcnt lgkmcnt(0)
	ds_read_b128 v[50:53], v221
	ds_read_b128 v[54:57], v221 offset:1088
	ds_read_b128 v[58:61], v221 offset:2176
	ds_read_b128 v[62:65], v221 offset:3264
	ds_read_b128 v[34:37], v221 offset:4352
	ds_read_b128 v[38:41], v221 offset:5440
	ds_read_b128 v[42:45], v221 offset:6528
	ds_read_b128 v[46:49], v221 offset:7616
	s_waitcnt lgkmcnt(7)
	s_and_saveexec_b64 s[88:89], s[66:67]
	global_store_dwordx4 v238, v[50:53], s[86:87] nt
	s_mov_b64 exec, s[88:89]
	s_nop 1
	v_cvt_pk_bf16_f32 v50, v50, v51
	v_cvt_pk_bf16_f32 v51, v52, v53
	global_store_dwordx2 v230, v[50:51], s[82:83]
	s_waitcnt lgkmcnt(6)
	s_and_saveexec_b64 s[88:89], s[68:69]
	global_store_dwordx4 v239, v[54:57], s[86:87] nt
	s_mov_b64 exec, s[88:89]
	s_nop 1
	v_cvt_pk_bf16_f32 v54, v54, v55
	v_cvt_pk_bf16_f32 v55, v56, v57
	global_store_dwordx2 v231, v[54:55], s[82:83]
	s_waitcnt lgkmcnt(5)
	s_and_saveexec_b64 s[88:89], s[70:71]
	global_store_dwordx4 v240, v[58:61], s[86:87] nt
	s_mov_b64 exec, s[88:89]
	s_nop 1
	v_cvt_pk_bf16_f32 v58, v58, v59
	v_cvt_pk_bf16_f32 v59, v60, v61
	global_store_dwordx2 v232, v[58:59], s[82:83]
	s_waitcnt lgkmcnt(4)
	s_and_saveexec_b64 s[88:89], s[72:73]
	global_store_dwordx4 v241, v[62:65], s[86:87] nt
	s_mov_b64 exec, s[88:89]
	s_nop 1
	v_cvt_pk_bf16_f32 v62, v62, v63
	v_cvt_pk_bf16_f32 v63, v64, v65
	global_store_dwordx2 v233, v[62:63], s[82:83]
	s_waitcnt lgkmcnt(3)
	s_and_saveexec_b64 s[88:89], s[74:75]
	global_store_dwordx4 v242, v[34:37], s[86:87] nt
	s_mov_b64 exec, s[88:89]
	s_nop 1
	v_cvt_pk_bf16_f32 v34, v34, v35
	v_cvt_pk_bf16_f32 v35, v36, v37
	global_store_dwordx2 v234, v[34:35], s[82:83]
	s_waitcnt lgkmcnt(2)
	s_and_saveexec_b64 s[88:89], s[76:77]
	global_store_dwordx4 v243, v[38:41], s[86:87] nt
	s_mov_b64 exec, s[88:89]
	s_nop 1
	v_cvt_pk_bf16_f32 v38, v38, v39
	v_cvt_pk_bf16_f32 v39, v40, v41
	global_store_dwordx2 v235, v[38:39], s[82:83]
	s_waitcnt lgkmcnt(1)
	s_and_saveexec_b64 s[88:89], s[78:79]
	global_store_dwordx4 v244, v[42:45], s[86:87] nt
	s_mov_b64 exec, s[88:89]
	s_nop 1
	v_cvt_pk_bf16_f32 v42, v42, v43
	v_cvt_pk_bf16_f32 v43, v44, v45
	global_store_dwordx2 v236, v[42:43], s[82:83]
	s_waitcnt lgkmcnt(0)
	s_and_saveexec_b64 s[88:89], s[80:81]
	global_store_dwordx4 v245, v[46:49], s[86:87] nt
	s_mov_b64 exec, s[88:89]
	s_nop 1
	v_cvt_pk_bf16_f32 v46, v46, v47
	v_cvt_pk_bf16_f32 v47, v48, v49
	global_store_dwordx2 v237, v[46:47], s[82:83]
	ds_write_b128 v220, v[18:21]
	ds_write_b128 v220, v[22:25] offset:32
	ds_write_b128 v220, v[26:29] offset:64
	ds_write_b128 v220, v[30:33] offset:96
	ds_write_b128 v220, v[2:5] offset:128
	ds_write_b128 v220, v[6:9] offset:160
	ds_write_b128 v220, v[10:13] offset:192
	ds_write_b128 v220, v[14:17] offset:224
	v_add_u32_e32 v226, 64, v222
	v_lshlrev_b32_e32 v238, 12, v226
	v_lshl_add_u32 v238, v225, 1, v238
	v_cmp_gt_i32_e64 s[66:67], s90, v226
	v_add_u32_e32 v227, 0xfffff000, v226
	v_ashrrev_i32_e32 v227, 11, v227
	v_add_u32_e32 v227, 1, v227
	v_max_i32_e32 v227, 0, v227
	v_lshl_add_u32 v226, v227, 8, v226
	v_lshl_add_u32 v230, v226, 11, v225
	v_add_u32_e32 v226, 68, v222
	v_lshlrev_b32_e32 v239, 12, v226
	v_lshl_add_u32 v239, v225, 1, v239
	v_cmp_gt_i32_e64 s[68:69], s90, v226
	v_add_u32_e32 v227, 0xfffff000, v226
	v_ashrrev_i32_e32 v227, 11, v227
	v_add_u32_e32 v227, 1, v227
	v_max_i32_e32 v227, 0, v227
	v_lshl_add_u32 v226, v227, 8, v226
	v_lshl_add_u32 v231, v226, 11, v225
	v_add_u32_e32 v226, 72, v222
	v_lshlrev_b32_e32 v240, 12, v226
	v_lshl_add_u32 v240, v225, 1, v240
	v_cmp_gt_i32_e64 s[70:71], s90, v226
	v_add_u32_e32 v227, 0xfffff000, v226
	v_ashrrev_i32_e32 v227, 11, v227
	v_add_u32_e32 v227, 1, v227
	v_max_i32_e32 v227, 0, v227
	v_lshl_add_u32 v226, v227, 8, v226
	v_lshl_add_u32 v232, v226, 11, v225
	v_add_u32_e32 v226, 76, v222
	v_lshlrev_b32_e32 v241, 12, v226
	v_lshl_add_u32 v241, v225, 1, v241
	v_cmp_gt_i32_e64 s[72:73], s90, v226
	v_add_u32_e32 v227, 0xfffff000, v226
	v_ashrrev_i32_e32 v227, 11, v227
	v_add_u32_e32 v227, 1, v227
	v_max_i32_e32 v227, 0, v227
	v_lshl_add_u32 v226, v227, 8, v226
	v_lshl_add_u32 v233, v226, 11, v225
	v_add_u32_e32 v226, 80, v222
	v_lshlrev_b32_e32 v242, 12, v226
	v_lshl_add_u32 v242, v225, 1, v242
	v_cmp_gt_i32_e64 s[74:75], s90, v226
	v_add_u32_e32 v227, 0xfffff000, v226
	v_ashrrev_i32_e32 v227, 11, v227
	v_add_u32_e32 v227, 1, v227
	v_max_i32_e32 v227, 0, v227
	v_lshl_add_u32 v226, v227, 8, v226
	v_lshl_add_u32 v234, v226, 11, v225
	v_add_u32_e32 v226, 84, v222
	v_lshlrev_b32_e32 v243, 12, v226
	v_lshl_add_u32 v243, v225, 1, v243
	v_cmp_gt_i32_e64 s[76:77], s90, v226
	v_add_u32_e32 v227, 0xfffff000, v226
	v_ashrrev_i32_e32 v227, 11, v227
	v_add_u32_e32 v227, 1, v227
	v_max_i32_e32 v227, 0, v227
	v_lshl_add_u32 v226, v227, 8, v226
	v_lshl_add_u32 v235, v226, 11, v225
	v_add_u32_e32 v226, 88, v222
	v_lshlrev_b32_e32 v244, 12, v226
	v_lshl_add_u32 v244, v225, 1, v244
	v_cmp_gt_i32_e64 s[78:79], s90, v226
	v_add_u32_e32 v227, 0xfffff000, v226
	v_ashrrev_i32_e32 v227, 11, v227
	v_add_u32_e32 v227, 1, v227
	v_max_i32_e32 v227, 0, v227
	v_lshl_add_u32 v226, v227, 8, v226
	v_lshl_add_u32 v236, v226, 11, v225
	v_add_u32_e32 v226, 92, v222
	v_lshlrev_b32_e32 v245, 12, v226
	v_lshl_add_u32 v245, v225, 1, v245
	v_cmp_gt_i32_e64 s[80:81], s90, v226
	v_add_u32_e32 v227, 0xfffff000, v226
	v_ashrrev_i32_e32 v227, 11, v227
	v_add_u32_e32 v227, 1, v227
	v_max_i32_e32 v227, 0, v227
	v_lshl_add_u32 v226, v227, 8, v226
	v_lshl_add_u32 v237, v226, 11, v225
	s_waitcnt lgkmcnt(0)
	ds_read_b128 v[18:21], v221
	ds_read_b128 v[22:25], v221 offset:1088
	ds_read_b128 v[26:29], v221 offset:2176
	ds_read_b128 v[30:33], v221 offset:3264
	ds_read_b128 v[2:5], v221 offset:4352
	ds_read_b128 v[6:9], v221 offset:5440
	ds_read_b128 v[10:13], v221 offset:6528
	ds_read_b128 v[14:17], v221 offset:7616
	s_waitcnt lgkmcnt(7)
	s_and_saveexec_b64 s[88:89], s[66:67]
	global_store_dwordx4 v238, v[18:21], s[86:87] nt
	s_mov_b64 exec, s[88:89]
	s_nop 1
	v_cvt_pk_bf16_f32 v18, v18, v19
	v_cvt_pk_bf16_f32 v19, v20, v21
	global_store_dwordx2 v230, v[18:19], s[82:83]
	s_waitcnt lgkmcnt(6)
	s_and_saveexec_b64 s[88:89], s[68:69]
	global_store_dwordx4 v239, v[22:25], s[86:87] nt
	s_mov_b64 exec, s[88:89]
	s_nop 1
	v_cvt_pk_bf16_f32 v22, v22, v23
	v_cvt_pk_bf16_f32 v23, v24, v25
	global_store_dwordx2 v231, v[22:23], s[82:83]
	s_waitcnt lgkmcnt(5)
	s_and_saveexec_b64 s[88:89], s[70:71]
	global_store_dwordx4 v240, v[26:29], s[86:87] nt
	s_mov_b64 exec, s[88:89]
	s_nop 1
	v_cvt_pk_bf16_f32 v26, v26, v27
	v_cvt_pk_bf16_f32 v27, v28, v29
	global_store_dwordx2 v232, v[26:27], s[82:83]
	s_waitcnt lgkmcnt(4)
	s_and_saveexec_b64 s[88:89], s[72:73]
	global_store_dwordx4 v241, v[30:33], s[86:87] nt
	s_mov_b64 exec, s[88:89]
	s_nop 1
	v_cvt_pk_bf16_f32 v30, v30, v31
	v_cvt_pk_bf16_f32 v31, v32, v33
	global_store_dwordx2 v233, v[30:31], s[82:83]
	s_waitcnt lgkmcnt(3)
	s_and_saveexec_b64 s[88:89], s[74:75]
	global_store_dwordx4 v242, v[2:5], s[86:87] nt
	s_mov_b64 exec, s[88:89]
	s_nop 1
	v_cvt_pk_bf16_f32 v2, v2, v3
	v_cvt_pk_bf16_f32 v3, v4, v5
	global_store_dwordx2 v234, v[2:3], s[82:83]
	s_waitcnt lgkmcnt(2)
	s_and_saveexec_b64 s[88:89], s[76:77]
	global_store_dwordx4 v243, v[6:9], s[86:87] nt
	s_mov_b64 exec, s[88:89]
	s_nop 1
	v_cvt_pk_bf16_f32 v6, v6, v7
	v_cvt_pk_bf16_f32 v7, v8, v9
	global_store_dwordx2 v235, v[6:7], s[82:83]
	s_waitcnt lgkmcnt(1)
	s_and_saveexec_b64 s[88:89], s[78:79]
	global_store_dwordx4 v244, v[10:13], s[86:87] nt
	s_mov_b64 exec, s[88:89]
	s_nop 1
	v_cvt_pk_bf16_f32 v10, v10, v11
	v_cvt_pk_bf16_f32 v11, v12, v13
	global_store_dwordx2 v236, v[10:11], s[82:83]
	s_waitcnt lgkmcnt(0)
	s_and_saveexec_b64 s[88:89], s[80:81]
	global_store_dwordx4 v245, v[14:17], s[86:87] nt
	s_mov_b64 exec, s[88:89]
	s_nop 1
	v_cvt_pk_bf16_f32 v14, v14, v15
	v_cvt_pk_bf16_f32 v15, v16, v17
	global_store_dwordx2 v237, v[14:15], s[82:83]
	s_barrier
	s_branch .LBB0_1266
G1E_ph13_NK2:
	v_and_b32_e32 v223, 31, v0
	v_mul_u32_u24_e32 v220, 0x110, v223
	v_bfe_u32 v223, v0, 5, 1
	v_lshl_add_u32 v220, v223, 4, v220
	v_bfe_u32 v224, v0, 6, 2
	v_mul_u32_u24_e32 v223, 0x2200, v224
	v_add_u32_e32 v220, v220, v223
	v_bfe_u32 v222, v0, 4, 2
	v_mul_u32_u24_e32 v221, 0x110, v222
	v_add_u32_e32 v221, v221, v223
	v_and_b32_e32 v223, 15, v0
	v_lshl_add_u32 v221, v223, 4, v221
	s_lshr_b32 s85, s64, 6
	s_sub_u32 s85, s85, 8
	s_lshl_b32 s85, s85, 8
	s_and_b32 s84, s64, 63
	s_mulk_i32 s84, 0xc0
	v_lshrrev_b32_e32 v224, 1, v224
	v_mul_u32_u24_e32 v224, 0x60, v224
	v_add3_u32 v222, v222, v224, s84
	v_lshlrev_b32_e32 v225, 3, v223
	v_bfe_u32 v223, v0, 6, 1
	v_lshl_add_u32 v225, v223, 7, v225
	v_add_u32_e32 v225, s85, v225
	ds_write_b128 v220, v[82:85]
	ds_write_b128 v220, v[86:89] offset:32
	ds_write_b128 v220, v[90:93] offset:64
	ds_write_b128 v220, v[94:97] offset:96
	ds_write_b128 v220, v[66:69] offset:128
	ds_write_b128 v220, v[70:73] offset:160
	ds_write_b128 v220, v[74:77] offset:192
	ds_write_b128 v220, v[78:81] offset:224
	v_add_u32_e32 v226, 0, v222
	v_add_u32_e32 v227, 0xfffff000, v226
	v_ashrrev_i32_e32 v227, 11, v227
	v_add_u32_e32 v227, 1, v227
	v_max_i32_e32 v227, 0, v227
	v_lshl_add_u32 v226, v227, 8, v226
	v_lshl_add_u32 v230, v226, 11, v225
	v_add_u32_e32 v226, 4, v222
	v_add_u32_e32 v227, 0xfffff000, v226
	v_ashrrev_i32_e32 v227, 11, v227
	v_add_u32_e32 v227, 1, v227
	v_max_i32_e32 v227, 0, v227
	v_lshl_add_u32 v226, v227, 8, v226
	v_lshl_add_u32 v231, v226, 11, v225
	v_add_u32_e32 v226, 8, v222
	v_add_u32_e32 v227, 0xfffff000, v226
	v_ashrrev_i32_e32 v227, 11, v227
	v_add_u32_e32 v227, 1, v227
	v_max_i32_e32 v227, 0, v227
	v_lshl_add_u32 v226, v227, 8, v226
	v_lshl_add_u32 v232, v226, 11, v225
	v_add_u32_e32 v226, 12, v222
	v_add_u32_e32 v227, 0xfffff000, v226
	v_ashrrev_i32_e32 v227, 11, v227
	v_add_u32_e32 v227, 1, v227
	v_max_i32_e32 v227, 0, v227
	v_lshl_add_u32 v226, v227, 8, v226
	v_lshl_add_u32 v233, v226, 11, v225
	v_add_u32_e32 v226, 16, v222
	v_add_u32_e32 v227, 0xfffff000, v226
	v_ashrrev_i32_e32 v227, 11, v227
	v_add_u32_e32 v227, 1, v227
	v_max_i32_e32 v227, 0, v227
	v_lshl_add_u32 v226, v227, 8, v226
	v_lshl_add_u32 v234, v226, 11, v225
	v_add_u32_e32 v226, 20, v222
	v_add_u32_e32 v227, 0xfffff000, v226
	v_ashrrev_i32_e32 v227, 11, v227
	v_add_u32_e32 v227, 1, v227
	v_max_i32_e32 v227, 0, v227
	v_lshl_add_u32 v226, v227, 8, v226
	v_lshl_add_u32 v235, v226, 11, v225
	v_add_u32_e32 v226, 24, v222
	v_add_u32_e32 v227, 0xfffff000, v226
	v_ashrrev_i32_e32 v227, 11, v227
	v_add_u32_e32 v227, 1, v227
	v_max_i32_e32 v227, 0, v227
	v_lshl_add_u32 v226, v227, 8, v226
	v_lshl_add_u32 v236, v226, 11, v225
	v_add_u32_e32 v226, 28, v222
	v_add_u32_e32 v227, 0xfffff000, v226
	v_ashrrev_i32_e32 v227, 11, v227
	v_add_u32_e32 v227, 1, v227
	v_max_i32_e32 v227, 0, v227
	v_lshl_add_u32 v226, v227, 8, v226
	v_lshl_add_u32 v237, v226, 11, v225
	s_waitcnt lgkmcnt(0)
	ds_read_b128 v[82:85], v221
	ds_read_b128 v[86:89], v221 offset:1088
	ds_read_b128 v[90:93], v221 offset:2176
	ds_read_b128 v[94:97], v221 offset:3264
	ds_read_b128 v[66:69], v221 offset:4352
	ds_read_b128 v[70:73], v221 offset:5440
	ds_read_b128 v[74:77], v221 offset:6528
	ds_read_b128 v[78:81], v221 offset:7616
	s_waitcnt lgkmcnt(7)
	v_cvt_pk_bf16_f32 v82, v82, v83
	v_cvt_pk_bf16_f32 v83, v84, v85
	global_store_dwordx2 v230, v[82:83], s[82:83]
	s_waitcnt lgkmcnt(6)
	v_cvt_pk_bf16_f32 v86, v86, v87
	v_cvt_pk_bf16_f32 v87, v88, v89
	global_store_dwordx2 v231, v[86:87], s[82:83]
	s_waitcnt lgkmcnt(5)
	v_cvt_pk_bf16_f32 v90, v90, v91
	v_cvt_pk_bf16_f32 v91, v92, v93
	global_store_dwordx2 v232, v[90:91], s[82:83]
	s_waitcnt lgkmcnt(4)
	v_cvt_pk_bf16_f32 v94, v94, v95
	v_cvt_pk_bf16_f32 v95, v96, v97
	global_store_dwordx2 v233, v[94:95], s[82:83]
	s_waitcnt lgkmcnt(3)
	v_cvt_pk_bf16_f32 v66, v66, v67
	v_cvt_pk_bf16_f32 v67, v68, v69
	global_store_dwordx2 v234, v[66:67], s[82:83]
	s_waitcnt lgkmcnt(2)
	v_cvt_pk_bf16_f32 v70, v70, v71
	v_cvt_pk_bf16_f32 v71, v72, v73
	global_store_dwordx2 v235, v[70:71], s[82:83]
	s_waitcnt lgkmcnt(1)
	v_cvt_pk_bf16_f32 v74, v74, v75
	v_cvt_pk_bf16_f32 v75, v76, v77
	global_store_dwordx2 v236, v[74:75], s[82:83]
	s_waitcnt lgkmcnt(0)
	v_cvt_pk_bf16_f32 v78, v78, v79
	v_cvt_pk_bf16_f32 v79, v80, v81
	global_store_dwordx2 v237, v[78:79], s[82:83]
	ds_write_b128 v220, v[50:53]
	ds_write_b128 v220, v[54:57] offset:32
	ds_write_b128 v220, v[58:61] offset:64
	ds_write_b128 v220, v[62:65] offset:96
	ds_write_b128 v220, v[34:37] offset:128
	ds_write_b128 v220, v[38:41] offset:160
	ds_write_b128 v220, v[42:45] offset:192
	ds_write_b128 v220, v[46:49] offset:224
	v_add_u32_e32 v226, 32, v222
	v_add_u32_e32 v227, 0xfffff000, v226
	v_ashrrev_i32_e32 v227, 11, v227
	v_add_u32_e32 v227, 1, v227
	v_max_i32_e32 v227, 0, v227
	v_lshl_add_u32 v226, v227, 8, v226
	v_lshl_add_u32 v230, v226, 11, v225
	v_add_u32_e32 v226, 36, v222
	v_add_u32_e32 v227, 0xfffff000, v226
	v_ashrrev_i32_e32 v227, 11, v227
	v_add_u32_e32 v227, 1, v227
	v_max_i32_e32 v227, 0, v227
	v_lshl_add_u32 v226, v227, 8, v226
	v_lshl_add_u32 v231, v226, 11, v225
	v_add_u32_e32 v226, 40, v222
	v_add_u32_e32 v227, 0xfffff000, v226
	v_ashrrev_i32_e32 v227, 11, v227
	v_add_u32_e32 v227, 1, v227
	v_max_i32_e32 v227, 0, v227
	v_lshl_add_u32 v226, v227, 8, v226
	v_lshl_add_u32 v232, v226, 11, v225
	v_add_u32_e32 v226, 44, v222
	v_add_u32_e32 v227, 0xfffff000, v226
	v_ashrrev_i32_e32 v227, 11, v227
	v_add_u32_e32 v227, 1, v227
	v_max_i32_e32 v227, 0, v227
	v_lshl_add_u32 v226, v227, 8, v226
	v_lshl_add_u32 v233, v226, 11, v225
	v_add_u32_e32 v226, 48, v222
	v_add_u32_e32 v227, 0xfffff000, v226
	v_ashrrev_i32_e32 v227, 11, v227
	v_add_u32_e32 v227, 1, v227
	v_max_i32_e32 v227, 0, v227
	v_lshl_add_u32 v226, v227, 8, v226
	v_lshl_add_u32 v234, v226, 11, v225
	v_add_u32_e32 v226, 52, v222
	v_add_u32_e32 v227, 0xfffff000, v226
	v_ashrrev_i32_e32 v227, 11, v227
	v_add_u32_e32 v227, 1, v227
	v_max_i32_e32 v227, 0, v227
	v_lshl_add_u32 v226, v227, 8, v226
	v_lshl_add_u32 v235, v226, 11, v225
	v_add_u32_e32 v226, 56, v222
	v_add_u32_e32 v227, 0xfffff000, v226
	v_ashrrev_i32_e32 v227, 11, v227
	v_add_u32_e32 v227, 1, v227
	v_max_i32_e32 v227, 0, v227
	v_lshl_add_u32 v226, v227, 8, v226
	v_lshl_add_u32 v236, v226, 11, v225
	v_add_u32_e32 v226, 60, v222
	v_add_u32_e32 v227, 0xfffff000, v226
	v_ashrrev_i32_e32 v227, 11, v227
	v_add_u32_e32 v227, 1, v227
	v_max_i32_e32 v227, 0, v227
	v_lshl_add_u32 v226, v227, 8, v226
	v_lshl_add_u32 v237, v226, 11, v225
	s_waitcnt lgkmcnt(0)
	ds_read_b128 v[50:53], v221
	ds_read_b128 v[54:57], v221 offset:1088
	ds_read_b128 v[58:61], v221 offset:2176
	ds_read_b128 v[62:65], v221 offset:3264
	ds_read_b128 v[34:37], v221 offset:4352
	ds_read_b128 v[38:41], v221 offset:5440
	ds_read_b128 v[42:45], v221 offset:6528
	ds_read_b128 v[46:49], v221 offset:7616
	s_waitcnt lgkmcnt(7)
	v_cvt_pk_bf16_f32 v50, v50, v51
	v_cvt_pk_bf16_f32 v51, v52, v53
	global_store_dwordx2 v230, v[50:51], s[82:83]
	s_waitcnt lgkmcnt(6)
	v_cvt_pk_bf16_f32 v54, v54, v55
	v_cvt_pk_bf16_f32 v55, v56, v57
	global_store_dwordx2 v231, v[54:55], s[82:83]
	s_waitcnt lgkmcnt(5)
	v_cvt_pk_bf16_f32 v58, v58, v59
	v_cvt_pk_bf16_f32 v59, v60, v61
	global_store_dwordx2 v232, v[58:59], s[82:83]
	s_waitcnt lgkmcnt(4)
	v_cvt_pk_bf16_f32 v62, v62, v63
	v_cvt_pk_bf16_f32 v63, v64, v65
	global_store_dwordx2 v233, v[62:63], s[82:83]
	s_waitcnt lgkmcnt(3)
	v_cvt_pk_bf16_f32 v34, v34, v35
	v_cvt_pk_bf16_f32 v35, v36, v37
	global_store_dwordx2 v234, v[34:35], s[82:83]
	s_waitcnt lgkmcnt(2)
	v_cvt_pk_bf16_f32 v38, v38, v39
	v_cvt_pk_bf16_f32 v39, v40, v41
	global_store_dwordx2 v235, v[38:39], s[82:83]
	s_waitcnt lgkmcnt(1)
	v_cvt_pk_bf16_f32 v42, v42, v43
	v_cvt_pk_bf16_f32 v43, v44, v45
	global_store_dwordx2 v236, v[42:43], s[82:83]
	s_waitcnt lgkmcnt(0)
	v_cvt_pk_bf16_f32 v46, v46, v47
	v_cvt_pk_bf16_f32 v47, v48, v49
	global_store_dwordx2 v237, v[46:47], s[82:83]
	ds_write_b128 v220, v[18:21]
	ds_write_b128 v220, v[22:25] offset:32
	ds_write_b128 v220, v[26:29] offset:64
	ds_write_b128 v220, v[30:33] offset:96
	ds_write_b128 v220, v[2:5] offset:128
	ds_write_b128 v220, v[6:9] offset:160
	ds_write_b128 v220, v[10:13] offset:192
	ds_write_b128 v220, v[14:17] offset:224
	v_add_u32_e32 v226, 64, v222
	v_add_u32_e32 v227, 0xfffff000, v226
	v_ashrrev_i32_e32 v227, 11, v227
	v_add_u32_e32 v227, 1, v227
	v_max_i32_e32 v227, 0, v227
	v_lshl_add_u32 v226, v227, 8, v226
	v_lshl_add_u32 v230, v226, 11, v225
	v_add_u32_e32 v226, 68, v222
	v_add_u32_e32 v227, 0xfffff000, v226
	v_ashrrev_i32_e32 v227, 11, v227
	v_add_u32_e32 v227, 1, v227
	v_max_i32_e32 v227, 0, v227
	v_lshl_add_u32 v226, v227, 8, v226
	v_lshl_add_u32 v231, v226, 11, v225
	v_add_u32_e32 v226, 72, v222
	v_add_u32_e32 v227, 0xfffff000, v226
	v_ashrrev_i32_e32 v227, 11, v227
	v_add_u32_e32 v227, 1, v227
	v_max_i32_e32 v227, 0, v227
	v_lshl_add_u32 v226, v227, 8, v226
	v_lshl_add_u32 v232, v226, 11, v225
	v_add_u32_e32 v226, 76, v222
	v_add_u32_e32 v227, 0xfffff000, v226
	v_ashrrev_i32_e32 v227, 11, v227
	v_add_u32_e32 v227, 1, v227
	v_max_i32_e32 v227, 0, v227
	v_lshl_add_u32 v226, v227, 8, v226
	v_lshl_add_u32 v233, v226, 11, v225
	v_add_u32_e32 v226, 80, v222
	v_add_u32_e32 v227, 0xfffff000, v226
	v_ashrrev_i32_e32 v227, 11, v227
	v_add_u32_e32 v227, 1, v227
	v_max_i32_e32 v227, 0, v227
	v_lshl_add_u32 v226, v227, 8, v226
	v_lshl_add_u32 v234, v226, 11, v225
	v_add_u32_e32 v226, 84, v222
	v_add_u32_e32 v227, 0xfffff000, v226
	v_ashrrev_i32_e32 v227, 11, v227
	v_add_u32_e32 v227, 1, v227
	v_max_i32_e32 v227, 0, v227
	v_lshl_add_u32 v226, v227, 8, v226
	v_lshl_add_u32 v235, v226, 11, v225
	v_add_u32_e32 v226, 88, v222
	v_add_u32_e32 v227, 0xfffff000, v226
	v_ashrrev_i32_e32 v227, 11, v227
	v_add_u32_e32 v227, 1, v227
	v_max_i32_e32 v227, 0, v227
	v_lshl_add_u32 v226, v227, 8, v226
	v_lshl_add_u32 v236, v226, 11, v225
	v_add_u32_e32 v226, 92, v222
	v_add_u32_e32 v227, 0xfffff000, v226
	v_ashrrev_i32_e32 v227, 11, v227
	v_add_u32_e32 v227, 1, v227
	v_max_i32_e32 v227, 0, v227
	v_lshl_add_u32 v226, v227, 8, v226
	v_lshl_add_u32 v237, v226, 11, v225
	s_waitcnt lgkmcnt(0)
	ds_read_b128 v[18:21], v221
	ds_read_b128 v[22:25], v221 offset:1088
	ds_read_b128 v[26:29], v221 offset:2176
	ds_read_b128 v[30:33], v221 offset:3264
	ds_read_b128 v[2:5], v221 offset:4352
	ds_read_b128 v[6:9], v221 offset:5440
	ds_read_b128 v[10:13], v221 offset:6528
	ds_read_b128 v[14:17], v221 offset:7616
	s_waitcnt lgkmcnt(7)
	v_cvt_pk_bf16_f32 v18, v18, v19
	v_cvt_pk_bf16_f32 v19, v20, v21
	global_store_dwordx2 v230, v[18:19], s[82:83]
	s_waitcnt lgkmcnt(6)
	v_cvt_pk_bf16_f32 v22, v22, v23
	v_cvt_pk_bf16_f32 v23, v24, v25
	global_store_dwordx2 v231, v[22:23], s[82:83]
	s_waitcnt lgkmcnt(5)
	v_cvt_pk_bf16_f32 v26, v26, v27
	v_cvt_pk_bf16_f32 v27, v28, v29
	global_store_dwordx2 v232, v[26:27], s[82:83]
	s_waitcnt lgkmcnt(4)
	v_cvt_pk_bf16_f32 v30, v30, v31
	v_cvt_pk_bf16_f32 v31, v32, v33
	global_store_dwordx2 v233, v[30:31], s[82:83]
	s_waitcnt lgkmcnt(3)
	v_cvt_pk_bf16_f32 v2, v2, v3
	v_cvt_pk_bf16_f32 v3, v4, v5
	global_store_dwordx2 v234, v[2:3], s[82:83]
	s_waitcnt lgkmcnt(2)
	v_cvt_pk_bf16_f32 v6, v6, v7
	v_cvt_pk_bf16_f32 v7, v8, v9
	global_store_dwordx2 v235, v[6:7], s[82:83]
	s_waitcnt lgkmcnt(1)
	v_cvt_pk_bf16_f32 v10, v10, v11
	v_cvt_pk_bf16_f32 v11, v12, v13
	global_store_dwordx2 v236, v[10:11], s[82:83]
	s_waitcnt lgkmcnt(0)
	v_cvt_pk_bf16_f32 v14, v14, v15
	v_cvt_pk_bf16_f32 v15, v16, v17
	global_store_dwordx2 v237, v[14:15], s[82:83]
	s_barrier
	s_branch .LBB0_1266
